# v73 + gate GEMM epilogue: xc loads of row blocks 1-7 issued up front, per-block vmcnt(0) dropped
# speedup vs baseline: 1.0039x; 1.0039x over previous
.LBB0_742:
	v_mbcnt_lo_u32_b32 v0, -1, 0
	v_mbcnt_hi_u32_b32 v0, -1, v0
	s_lshl_b32 s4, s73, 7
	v_readlane_b32 s5, v252, 33
	v_ashrrev_i32_e32 v46, 1, v0
	s_or_b32 s4, s4, s5
	v_and_b32_e32 v46, -8, v46
	v_add_u32_e32 v170, s4, v46
	v_ashrrev_i32_e32 v171, 31, v170
	v_lshlrev_b64 v[46:47], 2, v[170:171]
	v_lshl_add_u64 v[48:49], s[14:15], 0, v[46:47]
	global_load_dwordx4 v[154:157], v[48:49], off
	v_lshl_add_u64 v[50:51], s[10:11], 0, v[46:47]
	global_load_dwordx4 v[66:69], v[50:51], off
	s_lshl_b32 s4, s72, 8
	s_add_i32 s4, s4, s79
	v_and_or_b32 v0, v0, 15, s4
	v_lshlrev_b64 v[52:53], 11, v[0:1]
	v_lshl_add_u64 v[172:173], v[52:53], 0, v[170:171]
	v_lshl_add_u64 v[46:47], s[12:13], 0, v[46:47]
	v_lshl_add_u64 v[146:147], v[172:173], 1, s[0:1]
	global_load_dwordx4 v[150:153], v[48:49], off offset:16
	global_load_dwordx4 v[58:61], v[50:51], off offset:16
	s_nop 0
	global_load_dwordx4 v[50:53], v[46:47], off offset:16
	s_nop 0
	global_load_dwordx4 v[46:49], v[46:47], off
	s_nop 0
	global_load_dwordx4 v[146:149], v[146:147], off
	v_or_b32_e32 v230, 16, v0
	v_mov_b32_e32 v231, v1
	v_lshlrev_b64 v[230:231], 11, v[230:231]
	v_lshl_add_u64 v[230:231], v[230:231], 0, v[170:171]
	v_lshl_add_u64 v[230:231], v[230:231], 1, s[0:1]
	global_load_dwordx4 v[206:209], v[230:231], off
	v_or_b32_e32 v230, 32, v0
	v_mov_b32_e32 v231, v1
	v_lshlrev_b64 v[230:231], 11, v[230:231]
	v_lshl_add_u64 v[230:231], v[230:231], 0, v[170:171]
	v_lshl_add_u64 v[230:231], v[230:231], 1, s[0:1]
	global_load_dwordx4 v[210:213], v[230:231], off
	v_or_b32_e32 v230, 48, v0
	v_mov_b32_e32 v231, v1
	v_lshlrev_b64 v[230:231], 11, v[230:231]
	v_lshl_add_u64 v[230:231], v[230:231], 0, v[170:171]
	v_lshl_add_u64 v[230:231], v[230:231], 1, s[0:1]
	global_load_dwordx4 v[214:217], v[230:231], off
	v_add_u32_e32 v230, 0x80, v0
	v_mov_b32_e32 v231, v1
	v_lshlrev_b64 v[230:231], 11, v[230:231]
	v_lshl_add_u64 v[230:231], v[230:231], 0, v[170:171]
	v_lshl_add_u64 v[230:231], v[230:231], 1, s[0:1]
	global_load_dwordx4 v[218:221], v[230:231], off
	v_add_u32_e32 v230, 0x90, v0
	v_mov_b32_e32 v231, v1
	v_lshlrev_b64 v[230:231], 11, v[230:231]
	v_lshl_add_u64 v[230:231], v[230:231], 0, v[170:171]
	v_lshl_add_u64 v[230:231], v[230:231], 1, s[0:1]
	global_load_dwordx4 v[222:225], v[230:231], off
	v_add_u32_e32 v230, 0xa0, v0
	v_mov_b32_e32 v231, v1
	v_lshlrev_b64 v[230:231], 11, v[230:231]
	v_lshl_add_u64 v[230:231], v[230:231], 0, v[170:171]
	v_lshl_add_u64 v[230:231], v[230:231], 1, s[0:1]
	global_load_dwordx4 v[226:229], v[230:231], off
	v_add_u32_e32 v230, 0xb0, v0
	v_mov_b32_e32 v231, v1
	v_lshlrev_b64 v[230:231], 11, v[230:231]
	v_lshl_add_u64 v[230:231], v[230:231], 0, v[170:171]
	v_lshl_add_u64 v[230:231], v[230:231], 1, s[0:1]
	global_load_dwordx4 v[184:187], v[230:231], off
	s_waitcnt vmcnt(0)
	v_max_f32_e64 v176, -v154, -v154
	v_mul_f32_e64 v154, |v154|, s82
	v_exp_f32_e32 v154, v154
	v_add_f32_e32 v142, v142, v66
	v_mul_f32_e32 v142, 0xbfb8aa3b, v142
	v_exp_f32_e32 v142, v142
	v_add_f32_e32 v154, 1.0, v154
	v_cmp_gt_f32_e32 vcc, s81, v154
	v_max_f32_e32 v176, 0, v176
	v_add_f32_e32 v142, 1.0, v142
	v_cndmask_b32_e64 v177, 0, 32, vcc
	v_ldexp_f32 v154, v154, v177
	v_log_f32_e32 v154, v154
	v_cndmask_b32_e32 v177, 0, v203, vcc
	v_mul_f32_e32 v178, 0x3f317217, v154
	v_fma_f32 v178, v154, s65, -v178
	v_fmac_f32_e32 v178, 0x3377d1cf, v154
	v_fmac_f32_e32 v178, 0x3f317217, v154
	v_cmp_lt_f32_e64 vcc, |v154|, s56
	s_nop 1
	v_cndmask_b32_e32 v154, v154, v178, vcc
	v_rcp_f32_e32 v178, v142
	v_sub_f32_e32 v142, v154, v177
	v_add_f32_e32 v142, v176, v142
	v_mul_f32_e32 v142, 0xc1000000, v142
	v_mul_f32_e32 v154, v178, v142
	v_add_f32_e32 v177, v154, v154
	v_cmp_nlt_f32_e32 vcc, s83, v177
	s_and_saveexec_b64 s[4:5], vcc
	s_xor_b64 s[4:5], exec, s[4:5]
	v_mul_f32_e32 v176, 0x3fb8aa3b, v177
	v_exp_f32_e32 v176, v176
	s_nop 0
	v_sub_f32_e32 v176, 1.0, v176
	s_andn2_saveexec_b64 s[4:5], s[4:5]
	v_fmamk_f32 v176, v177, 0x3c088889, v199
	v_fmaak_f32 v176, v177, v176, 0x3e2aaaab
	v_fma_f32 v176, v177, v176, 0.5
	v_fma_f32 v176, v177, v176, 1.0
	v_mul_f32_e64 v176, v176, -v177
	s_or_b64 exec, exec, s[4:5]
	v_mul_f32_e64 v177, |v155|, s82
	v_exp_f32_e32 v177, v177
	v_add_f32_e32 v143, v143, v67
	v_mul_f32_e32 v143, 0xbfb8aa3b, v143
	v_exp_f32_e32 v143, v143
	v_add_f32_e32 v177, 1.0, v177
	v_cmp_gt_f32_e32 vcc, s81, v177
	v_max_f32_e64 v155, -v155, -v155
	v_add_f32_e32 v143, 1.0, v143
	v_cndmask_b32_e64 v178, 0, 32, vcc
	v_ldexp_f32 v177, v177, v178
	v_log_f32_e32 v177, v177
	v_rcp_f32_e32 v179, v143
	v_max_f32_e32 v155, 0, v155
	v_mul_f32_e32 v178, 0x3f317217, v177
	v_fma_f32 v178, v177, s65, -v178
	v_fmac_f32_e32 v178, 0x3377d1cf, v177
	v_fmac_f32_e32 v178, 0x3f317217, v177
	v_cmp_lt_f32_e64 s[4:5], |v177|, s56
	s_nop 1
	v_cndmask_b32_e64 v177, v177, v178, s[4:5]
	v_cndmask_b32_e32 v178, 0, v203, vcc
	v_sub_f32_e32 v143, v177, v178
	v_add_f32_e32 v143, v155, v143
	v_mul_f32_e32 v143, 0xc1000000, v143
	v_mul_f32_e32 v155, v179, v143
	v_add_f32_e32 v178, v155, v155
	v_cmp_nlt_f32_e32 vcc, s83, v178
	s_and_saveexec_b64 s[4:5], vcc
	s_xor_b64 s[4:5], exec, s[4:5]
	v_mul_f32_e32 v177, 0x3fb8aa3b, v178
	v_exp_f32_e32 v177, v177
	s_nop 0
	v_sub_f32_e32 v177, 1.0, v177
	s_andn2_saveexec_b64 s[4:5], s[4:5]
	v_fmamk_f32 v177, v178, 0x3c088889, v199
	v_fmaak_f32 v177, v178, v177, 0x3e2aaaab
	v_fma_f32 v177, v178, v177, 0.5
	v_fma_f32 v177, v178, v177, 1.0
	v_mul_f32_e64 v177, v177, -v178
	s_or_b64 exec, exec, s[4:5]
	v_mul_f32_e64 v178, |v156|, s82
	v_exp_f32_e32 v178, v178
	v_add_f32_e32 v144, v144, v68
	v_mul_f32_e32 v144, 0xbfb8aa3b, v144
	v_exp_f32_e32 v144, v144
	v_add_f32_e32 v178, 1.0, v178
	v_cmp_gt_f32_e32 vcc, s81, v178
	v_max_f32_e64 v156, -v156, -v156
	v_add_f32_e32 v144, 1.0, v144
	v_cndmask_b32_e64 v179, 0, 32, vcc
	v_ldexp_f32 v178, v178, v179
	v_log_f32_e32 v178, v178
	v_rcp_f32_e32 v180, v144
	v_max_f32_e32 v156, 0, v156
	v_mul_f32_e32 v179, 0x3f317217, v178
	v_fma_f32 v179, v178, s65, -v179
	v_fmac_f32_e32 v179, 0x3377d1cf, v178
	v_fmac_f32_e32 v179, 0x3f317217, v178
	v_cmp_lt_f32_e64 s[4:5], |v178|, s56
	s_nop 1
	v_cndmask_b32_e64 v178, v178, v179, s[4:5]
	v_cndmask_b32_e32 v179, 0, v203, vcc
	v_sub_f32_e32 v144, v178, v179
	v_add_f32_e32 v144, v156, v144
	v_mul_f32_e32 v144, 0xc1000000, v144
	v_mul_f32_e32 v156, v180, v144
	v_add_f32_e32 v179, v156, v156
	v_cmp_nlt_f32_e32 vcc, s83, v179
	s_and_saveexec_b64 s[4:5], vcc
	s_xor_b64 s[4:5], exec, s[4:5]
	v_mul_f32_e32 v178, 0x3fb8aa3b, v179
	v_exp_f32_e32 v178, v178
	s_nop 0
	v_sub_f32_e32 v178, 1.0, v178
	s_andn2_saveexec_b64 s[4:5], s[4:5]
	v_fmamk_f32 v178, v179, 0x3c088889, v199
	v_fmaak_f32 v178, v179, v178, 0x3e2aaaab
	v_fma_f32 v178, v179, v178, 0.5
	v_fma_f32 v178, v179, v178, 1.0
	v_mul_f32_e64 v178, v178, -v179
	s_or_b64 exec, exec, s[4:5]
	v_mul_f32_e64 v179, |v157|, s82
	v_exp_f32_e32 v179, v179
	v_add_f32_e32 v145, v145, v69
	v_mul_f32_e32 v145, 0xbfb8aa3b, v145
	v_exp_f32_e32 v145, v145
	v_add_f32_e32 v179, 1.0, v179
	v_cmp_gt_f32_e32 vcc, s81, v179
	v_max_f32_e64 v157, -v157, -v157
	v_add_f32_e32 v145, 1.0, v145
	v_cndmask_b32_e64 v180, 0, 32, vcc
	v_ldexp_f32 v179, v179, v180
	v_log_f32_e32 v179, v179
	v_rcp_f32_e32 v181, v145
	v_max_f32_e32 v157, 0, v157
	v_mul_f32_e32 v180, 0x3f317217, v179
	v_fma_f32 v180, v179, s65, -v180
	v_fmac_f32_e32 v180, 0x3377d1cf, v179
	v_fmac_f32_e32 v180, 0x3f317217, v179
	v_cmp_lt_f32_e64 s[4:5], |v179|, s56
	s_nop 1
	v_cndmask_b32_e64 v179, v179, v180, s[4:5]
	v_cndmask_b32_e32 v180, 0, v203, vcc
	v_sub_f32_e32 v145, v179, v180
	v_add_f32_e32 v145, v157, v145
	v_mul_f32_e32 v145, 0xc1000000, v145
	v_mul_f32_e32 v157, v181, v145
	v_add_f32_e32 v188, v157, v157
	v_cmp_nlt_f32_e32 vcc, s83, v188
	s_and_saveexec_b64 s[4:5], vcc
	s_xor_b64 s[4:5], exec, s[4:5]
	v_mul_f32_e32 v179, 0x3fb8aa3b, v188
	v_exp_f32_e32 v179, v179
	s_nop 0
	v_sub_f32_e32 v179, 1.0, v179
	s_andn2_saveexec_b64 s[4:5], s[4:5]
	v_fmamk_f32 v179, v188, 0x3c088889, v199
	v_fmaak_f32 v179, v188, v179, 0x3e2aaaab
	v_fma_f32 v179, v188, v179, 0.5
	v_fma_f32 v179, v188, v179, 1.0
	v_mul_f32_e64 v179, v179, -v188
	s_or_b64 exec, exec, s[4:5]
	v_mul_f32_e64 v180, |v150|, s82
	v_exp_f32_e32 v180, v180
	v_add_f32_e32 v138, v138, v58
	v_mul_f32_e32 v138, 0xbfb8aa3b, v138
	v_exp_f32_e32 v138, v138
	v_add_f32_e32 v180, 1.0, v180
	v_cmp_gt_f32_e32 vcc, s81, v180
	v_max_f32_e64 v150, -v150, -v150
	v_add_f32_e32 v138, 1.0, v138
	v_cndmask_b32_e64 v181, 0, 32, vcc
	v_ldexp_f32 v180, v180, v181
	v_log_f32_e32 v180, v180
	v_rcp_f32_e32 v182, v138
	v_max_f32_e32 v150, 0, v150
	v_mul_f32_e32 v181, 0x3f317217, v180
	v_fma_f32 v181, v180, s65, -v181
	v_fmac_f32_e32 v181, 0x3377d1cf, v180
	v_fmac_f32_e32 v181, 0x3f317217, v180
	v_cmp_lt_f32_e64 s[4:5], |v180|, s56
	s_nop 1
	v_cndmask_b32_e64 v180, v180, v181, s[4:5]
	v_cndmask_b32_e32 v181, 0, v203, vcc
	v_sub_f32_e32 v138, v180, v181
	v_add_f32_e32 v138, v150, v138
	v_mul_f32_e32 v138, 0xc1000000, v138
	v_mul_f32_e32 v150, v182, v138
	v_add_f32_e32 v189, v150, v150
	v_cmp_nlt_f32_e32 vcc, s83, v189
	s_and_saveexec_b64 s[4:5], vcc
	s_xor_b64 s[4:5], exec, s[4:5]
	v_mul_f32_e32 v180, 0x3fb8aa3b, v189
	v_exp_f32_e32 v180, v180
	s_nop 0
	v_sub_f32_e32 v188, 1.0, v180
	s_andn2_saveexec_b64 s[4:5], s[4:5]
	v_fmamk_f32 v180, v189, 0x3c088889, v199
	v_fmaak_f32 v180, v189, v180, 0x3e2aaaab
	v_fma_f32 v180, v189, v180, 0.5
	v_fma_f32 v180, v189, v180, 1.0
	v_mul_f32_e64 v188, v180, -v189
	s_or_b64 exec, exec, s[4:5]
	v_mul_f32_e64 v180, |v151|, s82
	v_exp_f32_e32 v180, v180
	v_add_f32_e32 v139, v139, v59
	v_mul_f32_e32 v139, 0xbfb8aa3b, v139
	v_exp_f32_e32 v139, v139
	v_add_f32_e32 v180, 1.0, v180
	v_cmp_gt_f32_e32 vcc, s81, v180
	v_max_f32_e64 v151, -v151, -v151
	v_add_f32_e32 v139, 1.0, v139
	v_cndmask_b32_e64 v181, 0, 32, vcc
	v_ldexp_f32 v180, v180, v181
	v_log_f32_e32 v180, v180
	v_rcp_f32_e32 v182, v139
	v_max_f32_e32 v151, 0, v151
	v_mul_f32_e32 v181, 0x3f317217, v180
	v_fma_f32 v181, v180, s65, -v181
	v_fmac_f32_e32 v181, 0x3377d1cf, v180
	v_fmac_f32_e32 v181, 0x3f317217, v180
	v_cmp_lt_f32_e64 s[4:5], |v180|, s56
	s_nop 1
	v_cndmask_b32_e64 v180, v180, v181, s[4:5]
	v_cndmask_b32_e32 v181, 0, v203, vcc
	v_sub_f32_e32 v139, v180, v181
	v_add_f32_e32 v139, v151, v139
	v_mul_f32_e32 v139, 0xc1000000, v139
	v_mul_f32_e32 v151, v182, v139
	v_add_f32_e32 v190, v151, v151
	v_cmp_nlt_f32_e32 vcc, s83, v190
	s_and_saveexec_b64 s[4:5], vcc
	s_xor_b64 s[4:5], exec, s[4:5]
	v_mul_f32_e32 v180, 0x3fb8aa3b, v190
	v_exp_f32_e32 v180, v180
	s_nop 0
	v_sub_f32_e32 v189, 1.0, v180
	s_andn2_saveexec_b64 s[4:5], s[4:5]
	v_fmamk_f32 v180, v190, 0x3c088889, v199
	v_fmaak_f32 v180, v190, v180, 0x3e2aaaab
	v_fma_f32 v180, v190, v180, 0.5
	v_fma_f32 v180, v190, v180, 1.0
	v_mul_f32_e64 v189, v180, -v190
	s_or_b64 exec, exec, s[4:5]
	v_mul_f32_e64 v180, |v152|, s82
	v_exp_f32_e32 v180, v180
	v_add_f32_e32 v140, v140, v60
	v_mul_f32_e32 v140, 0xbfb8aa3b, v140
	v_exp_f32_e32 v140, v140
	v_add_f32_e32 v180, 1.0, v180
	v_cmp_gt_f32_e32 vcc, s81, v180
	v_max_f32_e64 v152, -v152, -v152
	v_add_f32_e32 v140, 1.0, v140
	v_cndmask_b32_e64 v181, 0, 32, vcc
	v_ldexp_f32 v180, v180, v181
	v_log_f32_e32 v180, v180
	v_rcp_f32_e32 v182, v140
	v_max_f32_e32 v152, 0, v152
	v_mul_f32_e32 v181, 0x3f317217, v180
	v_fma_f32 v181, v180, s65, -v181
	v_fmac_f32_e32 v181, 0x3377d1cf, v180
	v_fmac_f32_e32 v181, 0x3f317217, v180
	v_cmp_lt_f32_e64 s[4:5], |v180|, s56
	s_nop 1
	v_cndmask_b32_e64 v180, v180, v181, s[4:5]
	v_cndmask_b32_e32 v181, 0, v203, vcc
	v_sub_f32_e32 v140, v180, v181
	v_add_f32_e32 v140, v152, v140
	v_mul_f32_e32 v140, 0xc1000000, v140
	v_mul_f32_e32 v152, v182, v140
	v_add_f32_e32 v190, v152, v152
	v_cmp_nlt_f32_e32 vcc, s83, v190
	s_and_saveexec_b64 s[4:5], vcc
	s_xor_b64 s[4:5], exec, s[4:5]
	v_mul_f32_e32 v180, 0x3fb8aa3b, v190
	v_exp_f32_e32 v180, v180
	s_nop 0
	v_sub_f32_e32 v191, 1.0, v180
	s_andn2_saveexec_b64 s[4:5], s[4:5]
	v_fmamk_f32 v180, v190, 0x3c088889, v199
	v_fmaak_f32 v180, v190, v180, 0x3e2aaaab
	v_fma_f32 v180, v190, v180, 0.5
	v_fma_f32 v180, v190, v180, 1.0
	v_mul_f32_e64 v191, v180, -v190
	s_or_b64 exec, exec, s[4:5]
	v_mul_f32_e64 v180, |v153|, s82
	v_exp_f32_e32 v180, v180
	v_add_f32_e32 v141, v141, v61
	v_mul_f32_e32 v141, 0xbfb8aa3b, v141
	v_exp_f32_e32 v141, v141
	v_add_f32_e32 v180, 1.0, v180
	v_cmp_gt_f32_e32 vcc, s81, v180
	v_max_f32_e64 v153, -v153, -v153
	v_add_f32_e32 v141, 1.0, v141
	v_cndmask_b32_e64 v181, 0, 32, vcc
	v_ldexp_f32 v180, v180, v181
	v_log_f32_e32 v180, v180
	v_rcp_f32_e32 v182, v141
	v_max_f32_e32 v153, 0, v153
	v_mul_f32_e32 v181, 0x3f317217, v180
	v_fma_f32 v181, v180, s65, -v181
	v_fmac_f32_e32 v181, 0x3377d1cf, v180
	v_fmac_f32_e32 v181, 0x3f317217, v180
	v_cmp_lt_f32_e64 s[4:5], |v180|, s56
	s_nop 1
	v_cndmask_b32_e64 v180, v180, v181, s[4:5]
	v_cndmask_b32_e32 v181, 0, v203, vcc
	v_sub_f32_e32 v141, v180, v181
	v_add_f32_e32 v141, v153, v141
	v_mul_f32_e32 v141, 0xc1000000, v141
	v_mul_f32_e32 v153, v182, v141
	v_add_f32_e32 v192, v153, v153
	v_cmp_nlt_f32_e32 vcc, s83, v192
	s_and_saveexec_b64 s[4:5], vcc
	s_xor_b64 s[4:5], exec, s[4:5]
	v_mul_f32_e32 v180, 0x3fb8aa3b, v192
	v_exp_f32_e32 v180, v180
	s_nop 0
	v_sub_f32_e32 v190, 1.0, v180
	s_andn2_saveexec_b64 s[4:5], s[4:5]
	v_fmamk_f32 v180, v192, 0x3c088889, v199
	v_fmaak_f32 v180, v192, v180, 0x3e2aaaab
	v_fma_f32 v180, v192, v180, 0.5
	v_fma_f32 v180, v192, v180, 1.0
	v_mul_f32_e64 v190, v180, -v192
	s_or_b64 exec, exec, s[4:5]
	v_add_f32_e32 v136, v136, v52
	v_mul_f32_e32 v136, 0xbfb8aa3b, v136
	v_exp_f32_e32 v136, v136
	v_add_f32_e32 v135, v135, v51
	v_mul_f32_e32 v135, 0xbfb8aa3b, v135
	v_add_f32_e32 v137, v137, v53
	v_add_f32_e32 v136, 1.0, v136
	v_exp_f32_e32 v135, v135
	v_rcp_f32_e32 v136, v136
	v_mul_f32_e32 v137, 0xbfb8aa3b, v137
	v_sqrt_f32_e32 v181, v191
	v_exp_f32_e32 v137, v137
	v_add_f32_e32 v134, v134, v50
	v_mul_f32_e32 v134, 0xbfb8aa3b, v134
	v_lshlrev_b32_e32 v180, 16, v149
	v_add_f32_e32 v135, 1.0, v135
	v_exp_f32_e32 v134, v134
	v_mul_f32_e32 v136, v136, v180
	v_rcp_f32_e32 v135, v135
	v_mul_f32_e32 v180, v136, v181
	v_add_f32_e32 v136, 1.0, v137
	v_sqrt_f32_e32 v137, v189
	v_add_f32_e32 v133, v133, v49
	v_mul_f32_e32 v133, 0xbfb8aa3b, v133
	v_and_b32_e32 v181, 0xffff0000, v148
	v_add_f32_e32 v134, 1.0, v134
	v_exp_f32_e32 v133, v133
	v_mul_f32_e32 v135, v135, v181
	v_rcp_f32_e32 v134, v134
	v_mul_f32_e32 v181, v135, v137
	v_sqrt_f32_e32 v135, v188
	v_add_f32_e32 v132, v132, v48
	v_mul_f32_e32 v132, 0xbfb8aa3b, v132
	v_lshlrev_b32_e32 v137, 16, v148
	v_add_f32_e32 v133, 1.0, v133
	v_exp_f32_e32 v132, v132
	v_mul_f32_e32 v134, v134, v137
	v_rcp_f32_e32 v133, v133
	v_mul_f32_e32 v148, v134, v135
	v_sqrt_f32_e32 v134, v179
	v_add_f32_e32 v131, v131, v47
	v_mul_f32_e32 v131, 0xbfb8aa3b, v131
	v_and_b32_e32 v135, 0xffff0000, v147
	v_add_f32_e32 v132, 1.0, v132
	v_exp_f32_e32 v131, v131
	v_mul_f32_e32 v133, v133, v135
	v_rcp_f32_e32 v132, v132
	v_add_f32_e32 v130, v130, v46
	v_mul_f32_e32 v179, v133, v134
	v_sqrt_f32_e32 v133, v178
	v_mul_f32_e32 v130, 0xbfb8aa3b, v130
	v_exp_f32_e32 v130, v130
	v_lshlrev_b32_e32 v134, 16, v147
	v_add_f32_e32 v131, 1.0, v131
	v_mul_f32_e32 v132, v132, v134
	v_rcp_f32_e32 v131, v131
	v_mul_f32_e32 v147, v132, v133
	v_sqrt_f32_e32 v133, v177
	v_add_f32_e32 v130, 1.0, v130
	v_and_b32_e32 v132, 0xffff0000, v146
	v_rcp_f32_e32 v130, v130
	v_mul_f32_e32 v131, v131, v132
	v_mul_f32_e32 v177, v131, v133
	v_sqrt_f32_e32 v131, v176
	v_rcp_f32_e32 v136, v136
	v_lshlrev_b32_e32 v132, 16, v146
	v_mul_f32_e32 v130, v130, v132
	v_sqrt_f32_e32 v132, v190
	v_mul_f32_e32 v146, v130, v131
	v_and_b32_e32 v130, 0xffff0000, v149
	v_mul_f32_e32 v130, v136, v130
	v_lshlrev_b64 v[134:135], 1, v[172:173]
	v_mul_f32_e32 v149, v130, v132
	v_lshl_add_u64 v[136:137], s[20:21], 0, v[134:135]
	v_cvt_pk_bf16_f32 v130, v154, v155
	v_cvt_pk_bf16_f32 v131, v156, v157
	v_cvt_pk_bf16_f32 v132, v150, v151
	v_cvt_pk_bf16_f32 v133, v152, v153
	global_store_dwordx4 v[136:137], v[130:133], off
	v_lshl_add_u64 v[134:135], s[22:23], 0, v[134:135]
	v_add_f32_e32 v126, v126, v66
	v_cvt_pk_bf16_f32 v130, v146, v177
	v_cvt_pk_bf16_f32 v131, v147, v179
	v_cvt_pk_bf16_f32 v132, v148, v181
	v_cvt_pk_bf16_f32 v133, v180, v149
	global_store_dwordx4 v[134:135], v[130:133], off
	v_mul_f32_e32 v126, 0xbfb8aa3b, v126
	v_exp_f32_e32 v126, v126
	v_or_b32_e32 v130, 16, v0
	v_mov_b32_e32 v131, v1
	v_lshlrev_b64 v[130:131], 11, v[130:131]
	v_lshl_add_u64 v[134:135], v[130:131], 0, v[170:171]
	v_lshl_add_u64 v[130:131], v[134:135], 1, s[0:1]
	v_mov_b32_e32 v130, v206
	v_mov_b32_e32 v131, v207
	v_mov_b32_e32 v132, v208
	v_mov_b32_e32 v133, v209
	v_add_f32_e32 v126, 1.0, v126
	v_rcp_f32_e32 v126, v126
	s_nop 0
	v_mul_f32_e32 v126, v126, v142
	v_add_f32_e32 v137, v126, v126
	v_cmp_nlt_f32_e32 vcc, s83, v137
	s_and_saveexec_b64 s[4:5], vcc
	s_xor_b64 s[4:5], exec, s[4:5]
	v_mul_f32_e32 v136, 0x3fb8aa3b, v137
	v_exp_f32_e32 v136, v136
	s_nop 0
	v_sub_f32_e32 v136, 1.0, v136
	s_andn2_saveexec_b64 s[4:5], s[4:5]
	v_fmamk_f32 v136, v137, 0x3c088889, v199
	v_fmaak_f32 v136, v137, v136, 0x3e2aaaab
	v_fma_f32 v136, v137, v136, 0.5
	v_fma_f32 v136, v137, v136, 1.0
	v_mul_f32_e64 v136, v136, -v137
	s_or_b64 exec, exec, s[4:5]
	v_add_f32_e32 v127, v127, v67
	v_mul_f32_e32 v127, 0xbfb8aa3b, v127
	v_exp_f32_e32 v127, v127
	s_nop 0
	v_add_f32_e32 v127, 1.0, v127
	v_rcp_f32_e32 v127, v127
	s_nop 0
	v_mul_f32_e32 v127, v127, v143
	v_add_f32_e32 v146, v127, v127
	v_cmp_nlt_f32_e32 vcc, s83, v146
	s_and_saveexec_b64 s[4:5], vcc
	s_xor_b64 s[4:5], exec, s[4:5]
	v_mul_f32_e32 v137, 0x3fb8aa3b, v146
	v_exp_f32_e32 v137, v137
	s_nop 0
	v_sub_f32_e32 v137, 1.0, v137
	s_andn2_saveexec_b64 s[4:5], s[4:5]
	v_fmamk_f32 v137, v146, 0x3c088889, v199
	v_fmaak_f32 v137, v146, v137, 0x3e2aaaab
	v_fma_f32 v137, v146, v137, 0.5
	v_fma_f32 v137, v146, v137, 1.0
	v_mul_f32_e64 v137, v137, -v146
	s_or_b64 exec, exec, s[4:5]
	v_add_f32_e32 v128, v128, v68
	v_mul_f32_e32 v128, 0xbfb8aa3b, v128
	v_exp_f32_e32 v128, v128
	s_nop 0
	v_add_f32_e32 v128, 1.0, v128
	v_rcp_f32_e32 v128, v128
	s_nop 0
	v_mul_f32_e32 v128, v128, v144
	v_add_f32_e32 v147, v128, v128
	v_cmp_nlt_f32_e32 vcc, s83, v147
	s_and_saveexec_b64 s[4:5], vcc
	s_xor_b64 s[4:5], exec, s[4:5]
	v_mul_f32_e32 v146, 0x3fb8aa3b, v147
	v_exp_f32_e32 v146, v146
	s_nop 0
	v_sub_f32_e32 v146, 1.0, v146
	s_andn2_saveexec_b64 s[4:5], s[4:5]
	v_fmamk_f32 v146, v147, 0x3c088889, v199
	v_fmaak_f32 v146, v147, v146, 0x3e2aaaab
	v_fma_f32 v146, v147, v146, 0.5
	v_fma_f32 v146, v147, v146, 1.0
	v_mul_f32_e64 v146, v146, -v147
	s_or_b64 exec, exec, s[4:5]
	v_add_f32_e32 v129, v129, v69
	v_mul_f32_e32 v129, 0xbfb8aa3b, v129
	v_exp_f32_e32 v129, v129
	s_nop 0
	v_add_f32_e32 v129, 1.0, v129
	v_rcp_f32_e32 v129, v129
	s_nop 0
	v_mul_f32_e32 v129, v129, v145
	v_add_f32_e32 v148, v129, v129
	v_cmp_nlt_f32_e32 vcc, s83, v148
	s_and_saveexec_b64 s[4:5], vcc
	s_xor_b64 s[4:5], exec, s[4:5]
	v_mul_f32_e32 v147, 0x3fb8aa3b, v148
	v_exp_f32_e32 v147, v147
	s_nop 0
	v_sub_f32_e32 v147, 1.0, v147
	s_andn2_saveexec_b64 s[4:5], s[4:5]
	v_fmamk_f32 v147, v148, 0x3c088889, v199
	v_fmaak_f32 v147, v148, v147, 0x3e2aaaab
	v_fma_f32 v147, v148, v147, 0.5
	v_fma_f32 v147, v148, v147, 1.0
	v_mul_f32_e64 v147, v147, -v148
	s_or_b64 exec, exec, s[4:5]
	v_add_f32_e32 v122, v122, v58
	v_mul_f32_e32 v122, 0xbfb8aa3b, v122
	v_exp_f32_e32 v122, v122
	s_nop 0
	v_add_f32_e32 v122, 1.0, v122
	v_rcp_f32_e32 v122, v122
	s_nop 0
	v_mul_f32_e32 v122, v122, v138
	v_add_f32_e32 v149, v122, v122
	v_cmp_nlt_f32_e32 vcc, s83, v149
	s_and_saveexec_b64 s[4:5], vcc
	s_xor_b64 s[4:5], exec, s[4:5]
	v_mul_f32_e32 v148, 0x3fb8aa3b, v149
	v_exp_f32_e32 v148, v148
	s_nop 0
	v_sub_f32_e32 v148, 1.0, v148
	s_andn2_saveexec_b64 s[4:5], s[4:5]
	v_fmamk_f32 v148, v149, 0x3c088889, v199
	v_fmaak_f32 v148, v149, v148, 0x3e2aaaab
	v_fma_f32 v148, v149, v148, 0.5
	v_fma_f32 v148, v149, v148, 1.0
	v_mul_f32_e64 v148, v148, -v149
	s_or_b64 exec, exec, s[4:5]
	v_add_f32_e32 v123, v123, v59
	v_mul_f32_e32 v123, 0xbfb8aa3b, v123
	v_exp_f32_e32 v123, v123
	s_nop 0
	v_add_f32_e32 v123, 1.0, v123
	v_rcp_f32_e32 v123, v123
	s_nop 0
	v_mul_f32_e32 v123, v123, v139
	v_add_f32_e32 v150, v123, v123
	v_cmp_nlt_f32_e32 vcc, s83, v150
	s_and_saveexec_b64 s[4:5], vcc
	s_xor_b64 s[4:5], exec, s[4:5]
	v_mul_f32_e32 v149, 0x3fb8aa3b, v150
	v_exp_f32_e32 v149, v149
	s_nop 0
	v_sub_f32_e32 v149, 1.0, v149
	s_andn2_saveexec_b64 s[4:5], s[4:5]
	v_fmamk_f32 v149, v150, 0x3c088889, v199
	v_fmaak_f32 v149, v150, v149, 0x3e2aaaab
	v_fma_f32 v149, v150, v149, 0.5
	v_fma_f32 v149, v150, v149, 1.0
	v_mul_f32_e64 v149, v149, -v150
	s_or_b64 exec, exec, s[4:5]
	v_add_f32_e32 v124, v124, v60
	v_mul_f32_e32 v124, 0xbfb8aa3b, v124
	v_exp_f32_e32 v124, v124
	s_nop 0
	v_add_f32_e32 v124, 1.0, v124
	v_rcp_f32_e32 v124, v124
	s_nop 0
	v_mul_f32_e32 v124, v124, v140
	v_add_f32_e32 v150, v124, v124
	v_cmp_nlt_f32_e32 vcc, s83, v150
	s_and_saveexec_b64 s[4:5], vcc
	s_xor_b64 s[4:5], exec, s[4:5]
	v_mul_f32_e32 v150, 0x3fb8aa3b, v150
	v_exp_f32_e32 v150, v150
	s_nop 0
	v_sub_f32_e32 v151, 1.0, v150
	s_andn2_saveexec_b64 s[4:5], s[4:5]
	v_fmamk_f32 v151, v150, 0x3c088889, v199
	v_fmaak_f32 v151, v150, v151, 0x3e2aaaab
	v_fma_f32 v151, v150, v151, 0.5
	v_fma_f32 v151, v150, v151, 1.0
	v_mul_f32_e64 v151, v151, -v150
	s_or_b64 exec, exec, s[4:5]
	v_add_f32_e32 v125, v125, v61
	v_mul_f32_e32 v125, 0xbfb8aa3b, v125
	v_exp_f32_e32 v125, v125
	s_nop 0
	v_add_f32_e32 v125, 1.0, v125
	v_rcp_f32_e32 v125, v125
	s_nop 0
	v_mul_f32_e32 v125, v125, v141
	v_add_f32_e32 v152, v125, v125
	v_cmp_nlt_f32_e32 vcc, s83, v152
	s_and_saveexec_b64 s[4:5], vcc
	s_xor_b64 s[4:5], exec, s[4:5]
	v_mul_f32_e32 v150, 0x3fb8aa3b, v152
	v_exp_f32_e32 v150, v150
	s_nop 0
	v_sub_f32_e32 v150, 1.0, v150
	s_andn2_saveexec_b64 s[4:5], s[4:5]
	v_fmamk_f32 v150, v152, 0x3c088889, v199
	v_fmaak_f32 v150, v152, v150, 0x3e2aaaab
	v_fma_f32 v150, v152, v150, 0.5
	v_fma_f32 v150, v152, v150, 1.0
	v_mul_f32_e64 v150, v150, -v152
	s_or_b64 exec, exec, s[4:5]
	v_add_f32_e32 v120, v120, v52
	v_mul_f32_e32 v120, 0xbfb8aa3b, v120
	v_exp_f32_e32 v120, v120
	v_add_f32_e32 v119, v119, v51
	v_mul_f32_e32 v119, 0xbfb8aa3b, v119
	v_add_f32_e32 v121, v121, v53
	v_add_f32_e32 v120, 1.0, v120
	v_exp_f32_e32 v119, v119
	v_rcp_f32_e32 v120, v120
	v_mul_f32_e32 v121, 0xbfb8aa3b, v121
	v_sqrt_f32_e32 v151, v151
	v_exp_f32_e32 v121, v121
	v_add_f32_e32 v118, v118, v50
	v_mul_f32_e32 v118, 0xbfb8aa3b, v118
	v_lshlrev_b32_e32 v152, 16, v133
	v_add_f32_e32 v119, 1.0, v119
	v_exp_f32_e32 v118, v118
	v_mul_f32_e32 v120, v120, v152
	v_rcp_f32_e32 v119, v119
	v_mul_f32_e32 v151, v120, v151
	v_add_f32_e32 v120, 1.0, v121
	v_sqrt_f32_e32 v121, v149
	v_add_f32_e32 v117, v117, v49
	v_mul_f32_e32 v117, 0xbfb8aa3b, v117
	v_and_b32_e32 v149, 0xffff0000, v132
	v_add_f32_e32 v118, 1.0, v118
	v_exp_f32_e32 v117, v117
	v_mul_f32_e32 v119, v119, v149
	v_rcp_f32_e32 v118, v118
	v_mul_f32_e32 v149, v119, v121
	v_sqrt_f32_e32 v119, v148
	v_add_f32_e32 v116, v116, v48
	v_mul_f32_e32 v116, 0xbfb8aa3b, v116
	v_lshlrev_b32_e32 v121, 16, v132
	v_add_f32_e32 v117, 1.0, v117
	v_exp_f32_e32 v116, v116
	v_mul_f32_e32 v118, v118, v121
	v_rcp_f32_e32 v117, v117
	v_mul_f32_e32 v132, v118, v119
	v_sqrt_f32_e32 v118, v147
	v_add_f32_e32 v115, v115, v47
	v_mul_f32_e32 v115, 0xbfb8aa3b, v115
	v_and_b32_e32 v119, 0xffff0000, v131
	v_add_f32_e32 v116, 1.0, v116
	v_exp_f32_e32 v115, v115
	v_mul_f32_e32 v117, v117, v119
	v_rcp_f32_e32 v116, v116
	v_add_f32_e32 v114, v114, v46
	v_mul_f32_e32 v147, v117, v118
	v_sqrt_f32_e32 v117, v146
	v_mul_f32_e32 v114, 0xbfb8aa3b, v114
	v_exp_f32_e32 v114, v114
	v_lshlrev_b32_e32 v118, 16, v131
	v_add_f32_e32 v115, 1.0, v115
	v_mul_f32_e32 v116, v116, v118
	v_rcp_f32_e32 v115, v115
	v_mul_f32_e32 v131, v116, v117
	v_sqrt_f32_e32 v117, v137
	v_add_f32_e32 v114, 1.0, v114
	v_and_b32_e32 v116, 0xffff0000, v130
	v_rcp_f32_e32 v114, v114
	v_mul_f32_e32 v115, v115, v116
	v_mul_f32_e32 v137, v115, v117
	v_sqrt_f32_e32 v115, v136
	v_rcp_f32_e32 v120, v120
	v_lshlrev_b32_e32 v116, 16, v130
	v_mul_f32_e32 v114, v114, v116
	v_sqrt_f32_e32 v116, v150
	v_mul_f32_e32 v130, v114, v115
	v_and_b32_e32 v114, 0xffff0000, v133
	v_mul_f32_e32 v114, v120, v114
	v_lshlrev_b64 v[118:119], 1, v[134:135]
	v_mul_f32_e32 v133, v114, v116
	v_lshl_add_u64 v[120:121], s[20:21], 0, v[118:119]
	v_cvt_pk_bf16_f32 v114, v126, v127
	v_cvt_pk_bf16_f32 v115, v128, v129
	v_cvt_pk_bf16_f32 v116, v122, v123
	v_cvt_pk_bf16_f32 v117, v124, v125
	global_store_dwordx4 v[120:121], v[114:117], off
	v_lshl_add_u64 v[118:119], s[22:23], 0, v[118:119]
	v_add_f32_e32 v110, v110, v66
	v_cvt_pk_bf16_f32 v114, v130, v137
	v_cvt_pk_bf16_f32 v115, v131, v147
	v_cvt_pk_bf16_f32 v116, v132, v149
	v_cvt_pk_bf16_f32 v117, v151, v133
	global_store_dwordx4 v[118:119], v[114:117], off
	v_mul_f32_e32 v110, 0xbfb8aa3b, v110
	v_exp_f32_e32 v110, v110
	v_or_b32_e32 v114, 32, v0
	v_mov_b32_e32 v115, v1
	v_lshlrev_b64 v[114:115], 11, v[114:115]
	v_lshl_add_u64 v[118:119], v[114:115], 0, v[170:171]
	v_lshl_add_u64 v[114:115], v[118:119], 1, s[0:1]
	v_mov_b32_e32 v114, v210
	v_mov_b32_e32 v115, v211
	v_mov_b32_e32 v116, v212
	v_mov_b32_e32 v117, v213
	v_add_f32_e32 v110, 1.0, v110
	v_rcp_f32_e32 v110, v110
	s_nop 0
	v_mul_f32_e32 v110, v110, v142
	v_add_f32_e32 v121, v110, v110
	v_cmp_nlt_f32_e32 vcc, s83, v121
	s_and_saveexec_b64 s[4:5], vcc
	s_xor_b64 s[4:5], exec, s[4:5]
	v_mul_f32_e32 v120, 0x3fb8aa3b, v121
	v_exp_f32_e32 v120, v120
	s_nop 0
	v_sub_f32_e32 v120, 1.0, v120
	s_andn2_saveexec_b64 s[4:5], s[4:5]
	v_fmamk_f32 v120, v121, 0x3c088889, v199
	v_fmaak_f32 v120, v121, v120, 0x3e2aaaab
	v_fma_f32 v120, v121, v120, 0.5
	v_fma_f32 v120, v121, v120, 1.0
	v_mul_f32_e64 v120, v120, -v121
	s_or_b64 exec, exec, s[4:5]
	v_add_f32_e32 v111, v111, v67
	v_mul_f32_e32 v111, 0xbfb8aa3b, v111
	v_exp_f32_e32 v111, v111
	s_nop 0
	v_add_f32_e32 v111, 1.0, v111
	v_rcp_f32_e32 v111, v111
	s_nop 0
	v_mul_f32_e32 v111, v111, v143
	v_add_f32_e32 v122, v111, v111
	v_cmp_nlt_f32_e32 vcc, s83, v122
	s_and_saveexec_b64 s[4:5], vcc
	s_xor_b64 s[4:5], exec, s[4:5]
	v_mul_f32_e32 v121, 0x3fb8aa3b, v122
	v_exp_f32_e32 v121, v121
	s_nop 0
	v_sub_f32_e32 v121, 1.0, v121
	s_andn2_saveexec_b64 s[4:5], s[4:5]
	v_fmamk_f32 v121, v122, 0x3c088889, v199
	v_fmaak_f32 v121, v122, v121, 0x3e2aaaab
	v_fma_f32 v121, v122, v121, 0.5
	v_fma_f32 v121, v122, v121, 1.0
	v_mul_f32_e64 v121, v121, -v122
	s_or_b64 exec, exec, s[4:5]
	v_add_f32_e32 v112, v112, v68
	v_mul_f32_e32 v112, 0xbfb8aa3b, v112
	v_exp_f32_e32 v112, v112
	s_nop 0
	v_add_f32_e32 v112, 1.0, v112
	v_rcp_f32_e32 v112, v112
	s_nop 0
	v_mul_f32_e32 v112, v112, v144
	v_add_f32_e32 v123, v112, v112
	v_cmp_nlt_f32_e32 vcc, s83, v123
	s_and_saveexec_b64 s[4:5], vcc
	s_xor_b64 s[4:5], exec, s[4:5]
	v_mul_f32_e32 v122, 0x3fb8aa3b, v123
	v_exp_f32_e32 v122, v122
	s_nop 0
	v_sub_f32_e32 v122, 1.0, v122
	s_andn2_saveexec_b64 s[4:5], s[4:5]
	v_fmamk_f32 v122, v123, 0x3c088889, v199
	v_fmaak_f32 v122, v123, v122, 0x3e2aaaab
	v_fma_f32 v122, v123, v122, 0.5
	v_fma_f32 v122, v123, v122, 1.0
	v_mul_f32_e64 v122, v122, -v123
	s_or_b64 exec, exec, s[4:5]
	v_add_f32_e32 v113, v113, v69
	v_mul_f32_e32 v113, 0xbfb8aa3b, v113
	v_exp_f32_e32 v113, v113
	s_nop 0
	v_add_f32_e32 v113, 1.0, v113
	v_rcp_f32_e32 v113, v113
	s_nop 0
	v_mul_f32_e32 v113, v113, v145
	v_add_f32_e32 v124, v113, v113
	v_cmp_nlt_f32_e32 vcc, s83, v124
	s_and_saveexec_b64 s[4:5], vcc
	s_xor_b64 s[4:5], exec, s[4:5]
	v_mul_f32_e32 v123, 0x3fb8aa3b, v124
	v_exp_f32_e32 v123, v123
	s_nop 0
	v_sub_f32_e32 v123, 1.0, v123
	s_andn2_saveexec_b64 s[4:5], s[4:5]
	v_fmamk_f32 v123, v124, 0x3c088889, v199
	v_fmaak_f32 v123, v124, v123, 0x3e2aaaab
	v_fma_f32 v123, v124, v123, 0.5
	v_fma_f32 v123, v124, v123, 1.0
	v_mul_f32_e64 v123, v123, -v124
	s_or_b64 exec, exec, s[4:5]
	v_add_f32_e32 v106, v106, v58
	v_mul_f32_e32 v106, 0xbfb8aa3b, v106
	v_exp_f32_e32 v106, v106
	s_nop 0
	v_add_f32_e32 v106, 1.0, v106
	v_rcp_f32_e32 v106, v106
	s_nop 0
	v_mul_f32_e32 v106, v106, v138
	v_add_f32_e32 v125, v106, v106
	v_cmp_nlt_f32_e32 vcc, s83, v125
	s_and_saveexec_b64 s[4:5], vcc
	s_xor_b64 s[4:5], exec, s[4:5]
	v_mul_f32_e32 v124, 0x3fb8aa3b, v125
	v_exp_f32_e32 v124, v124
	s_nop 0
	v_sub_f32_e32 v124, 1.0, v124
	s_andn2_saveexec_b64 s[4:5], s[4:5]
	v_fmamk_f32 v124, v125, 0x3c088889, v199
	v_fmaak_f32 v124, v125, v124, 0x3e2aaaab
	v_fma_f32 v124, v125, v124, 0.5
	v_fma_f32 v124, v125, v124, 1.0
	v_mul_f32_e64 v124, v124, -v125
	s_or_b64 exec, exec, s[4:5]
	v_add_f32_e32 v107, v107, v59
	v_mul_f32_e32 v107, 0xbfb8aa3b, v107
	v_exp_f32_e32 v107, v107
	s_nop 0
	v_add_f32_e32 v107, 1.0, v107
	v_rcp_f32_e32 v107, v107
	s_nop 0
	v_mul_f32_e32 v107, v107, v139
	v_add_f32_e32 v126, v107, v107
	v_cmp_nlt_f32_e32 vcc, s83, v126
	s_and_saveexec_b64 s[4:5], vcc
	s_xor_b64 s[4:5], exec, s[4:5]
	v_mul_f32_e32 v125, 0x3fb8aa3b, v126
	v_exp_f32_e32 v125, v125
	s_nop 0
	v_sub_f32_e32 v125, 1.0, v125
	s_andn2_saveexec_b64 s[4:5], s[4:5]
	v_fmamk_f32 v125, v126, 0x3c088889, v199
	v_fmaak_f32 v125, v126, v125, 0x3e2aaaab
	v_fma_f32 v125, v126, v125, 0.5
	v_fma_f32 v125, v126, v125, 1.0
	v_mul_f32_e64 v125, v125, -v126
	s_or_b64 exec, exec, s[4:5]
	v_add_f32_e32 v108, v108, v60
	v_mul_f32_e32 v108, 0xbfb8aa3b, v108
	v_exp_f32_e32 v108, v108
	s_nop 0
	v_add_f32_e32 v108, 1.0, v108
	v_rcp_f32_e32 v108, v108
	s_nop 0
	v_mul_f32_e32 v108, v108, v140
	v_add_f32_e32 v126, v108, v108
	v_cmp_nlt_f32_e32 vcc, s83, v126
	s_and_saveexec_b64 s[4:5], vcc
	s_xor_b64 s[4:5], exec, s[4:5]
	v_mul_f32_e32 v126, 0x3fb8aa3b, v126
	v_exp_f32_e32 v126, v126
	s_nop 0
	v_sub_f32_e32 v127, 1.0, v126
	s_andn2_saveexec_b64 s[4:5], s[4:5]
	v_fmamk_f32 v127, v126, 0x3c088889, v199
	v_fmaak_f32 v127, v126, v127, 0x3e2aaaab
	v_fma_f32 v127, v126, v127, 0.5
	v_fma_f32 v127, v126, v127, 1.0
	v_mul_f32_e64 v127, v127, -v126
	s_or_b64 exec, exec, s[4:5]
	v_add_f32_e32 v109, v109, v61
	v_mul_f32_e32 v109, 0xbfb8aa3b, v109
	v_exp_f32_e32 v109, v109
	s_nop 0
	v_add_f32_e32 v109, 1.0, v109
	v_rcp_f32_e32 v109, v109
	s_nop 0
	v_mul_f32_e32 v109, v109, v141
	v_add_f32_e32 v128, v109, v109
	v_cmp_nlt_f32_e32 vcc, s83, v128
	s_and_saveexec_b64 s[4:5], vcc
	s_xor_b64 s[4:5], exec, s[4:5]
	v_mul_f32_e32 v126, 0x3fb8aa3b, v128
	v_exp_f32_e32 v126, v126
	s_nop 0
	v_sub_f32_e32 v126, 1.0, v126
	s_andn2_saveexec_b64 s[4:5], s[4:5]
	v_fmamk_f32 v126, v128, 0x3c088889, v199
	v_fmaak_f32 v126, v128, v126, 0x3e2aaaab
	v_fma_f32 v126, v128, v126, 0.5
	v_fma_f32 v126, v128, v126, 1.0
	v_mul_f32_e64 v126, v126, -v128
	s_or_b64 exec, exec, s[4:5]
	v_add_f32_e32 v104, v104, v52
	v_mul_f32_e32 v104, 0xbfb8aa3b, v104
	v_exp_f32_e32 v104, v104
	v_add_f32_e32 v103, v103, v51
	v_mul_f32_e32 v103, 0xbfb8aa3b, v103
	v_add_f32_e32 v105, v105, v53
	v_add_f32_e32 v104, 1.0, v104
	v_exp_f32_e32 v103, v103
	v_rcp_f32_e32 v104, v104
	v_mul_f32_e32 v105, 0xbfb8aa3b, v105
	v_sqrt_f32_e32 v127, v127
	v_exp_f32_e32 v105, v105
	v_add_f32_e32 v102, v102, v50
	v_mul_f32_e32 v102, 0xbfb8aa3b, v102
	v_lshlrev_b32_e32 v128, 16, v117
	v_add_f32_e32 v103, 1.0, v103
	v_exp_f32_e32 v102, v102
	v_mul_f32_e32 v104, v104, v128
	v_rcp_f32_e32 v103, v103
	v_mul_f32_e32 v127, v104, v127
	v_add_f32_e32 v104, 1.0, v105
	v_sqrt_f32_e32 v105, v125
	v_add_f32_e32 v101, v101, v49
	v_mul_f32_e32 v101, 0xbfb8aa3b, v101
	v_and_b32_e32 v125, 0xffff0000, v116
	v_add_f32_e32 v102, 1.0, v102
	v_exp_f32_e32 v101, v101
	v_mul_f32_e32 v103, v103, v125
	v_rcp_f32_e32 v102, v102
	v_mul_f32_e32 v125, v103, v105
	v_sqrt_f32_e32 v103, v124
	v_add_f32_e32 v100, v100, v48
	v_mul_f32_e32 v100, 0xbfb8aa3b, v100
	v_lshlrev_b32_e32 v105, 16, v116
	v_add_f32_e32 v101, 1.0, v101
	v_exp_f32_e32 v100, v100
	v_mul_f32_e32 v102, v102, v105
	v_rcp_f32_e32 v101, v101
	v_mul_f32_e32 v116, v102, v103
	v_sqrt_f32_e32 v102, v123
	v_add_f32_e32 v99, v99, v47
	v_mul_f32_e32 v99, 0xbfb8aa3b, v99
	v_and_b32_e32 v103, 0xffff0000, v115
	v_add_f32_e32 v100, 1.0, v100
	v_exp_f32_e32 v99, v99
	v_mul_f32_e32 v101, v101, v103
	v_rcp_f32_e32 v100, v100
	v_add_f32_e32 v98, v98, v46
	v_mul_f32_e32 v123, v101, v102
	v_sqrt_f32_e32 v101, v122
	v_mul_f32_e32 v98, 0xbfb8aa3b, v98
	v_exp_f32_e32 v98, v98
	v_lshlrev_b32_e32 v102, 16, v115
	v_add_f32_e32 v99, 1.0, v99
	v_mul_f32_e32 v100, v100, v102
	v_rcp_f32_e32 v99, v99
	v_mul_f32_e32 v115, v100, v101
	v_sqrt_f32_e32 v101, v121
	v_add_f32_e32 v98, 1.0, v98
	v_and_b32_e32 v100, 0xffff0000, v114
	v_rcp_f32_e32 v98, v98
	v_mul_f32_e32 v99, v99, v100
	v_mul_f32_e32 v121, v99, v101
	v_sqrt_f32_e32 v99, v120
	v_rcp_f32_e32 v104, v104
	v_lshlrev_b32_e32 v100, 16, v114
	v_mul_f32_e32 v98, v98, v100
	v_sqrt_f32_e32 v100, v126
	v_mul_f32_e32 v114, v98, v99
	v_and_b32_e32 v98, 0xffff0000, v117
	v_mul_f32_e32 v98, v104, v98
	v_lshlrev_b64 v[102:103], 1, v[118:119]
	v_mul_f32_e32 v117, v98, v100
	v_lshl_add_u64 v[104:105], s[20:21], 0, v[102:103]
	v_cvt_pk_bf16_f32 v98, v110, v111
	v_cvt_pk_bf16_f32 v99, v112, v113
	v_cvt_pk_bf16_f32 v100, v106, v107
	v_cvt_pk_bf16_f32 v101, v108, v109
	global_store_dwordx4 v[104:105], v[98:101], off
	v_lshl_add_u64 v[102:103], s[22:23], 0, v[102:103]
	v_add_f32_e32 v94, v94, v66
	v_cvt_pk_bf16_f32 v98, v114, v121
	v_cvt_pk_bf16_f32 v99, v115, v123
	v_cvt_pk_bf16_f32 v100, v116, v125
	v_cvt_pk_bf16_f32 v101, v127, v117
	global_store_dwordx4 v[102:103], v[98:101], off
	v_mul_f32_e32 v94, 0xbfb8aa3b, v94
	v_exp_f32_e32 v94, v94
	v_or_b32_e32 v98, 48, v0
	v_mov_b32_e32 v99, v1
	v_lshlrev_b64 v[98:99], 11, v[98:99]
	v_lshl_add_u64 v[102:103], v[98:99], 0, v[170:171]
	v_lshl_add_u64 v[98:99], v[102:103], 1, s[0:1]
	v_mov_b32_e32 v98, v214
	v_mov_b32_e32 v99, v215
	v_mov_b32_e32 v100, v216
	v_mov_b32_e32 v101, v217
	v_add_f32_e32 v94, 1.0, v94
	v_rcp_f32_e32 v94, v94
	s_nop 0
	v_mul_f32_e32 v94, v94, v142
	v_add_f32_e32 v105, v94, v94
	v_cmp_nlt_f32_e32 vcc, s83, v105
	s_and_saveexec_b64 s[4:5], vcc
	s_xor_b64 s[4:5], exec, s[4:5]
	v_mul_f32_e32 v104, 0x3fb8aa3b, v105
	v_exp_f32_e32 v104, v104
	s_nop 0
	v_sub_f32_e32 v104, 1.0, v104
	s_andn2_saveexec_b64 s[4:5], s[4:5]
	v_fmamk_f32 v104, v105, 0x3c088889, v199
	v_fmaak_f32 v104, v105, v104, 0x3e2aaaab
	v_fma_f32 v104, v105, v104, 0.5
	v_fma_f32 v104, v105, v104, 1.0
	v_mul_f32_e64 v104, v104, -v105
	s_or_b64 exec, exec, s[4:5]
	v_add_f32_e32 v95, v95, v67
	v_mul_f32_e32 v95, 0xbfb8aa3b, v95
	v_exp_f32_e32 v95, v95
	s_nop 0
	v_add_f32_e32 v95, 1.0, v95
	v_rcp_f32_e32 v95, v95
	s_nop 0
	v_mul_f32_e32 v95, v95, v143
	v_add_f32_e32 v106, v95, v95
	v_cmp_nlt_f32_e32 vcc, s83, v106
	s_and_saveexec_b64 s[4:5], vcc
	s_xor_b64 s[4:5], exec, s[4:5]
	v_mul_f32_e32 v105, 0x3fb8aa3b, v106
	v_exp_f32_e32 v105, v105
	s_nop 0
	v_sub_f32_e32 v105, 1.0, v105
	s_andn2_saveexec_b64 s[4:5], s[4:5]
	v_fmamk_f32 v105, v106, 0x3c088889, v199
	v_fmaak_f32 v105, v106, v105, 0x3e2aaaab
	v_fma_f32 v105, v106, v105, 0.5
	v_fma_f32 v105, v106, v105, 1.0
	v_mul_f32_e64 v105, v105, -v106
	s_or_b64 exec, exec, s[4:5]
	v_add_f32_e32 v96, v96, v68
	v_mul_f32_e32 v96, 0xbfb8aa3b, v96
	v_exp_f32_e32 v96, v96
	s_nop 0
	v_add_f32_e32 v96, 1.0, v96
	v_rcp_f32_e32 v96, v96
	s_nop 0
	v_mul_f32_e32 v96, v96, v144
	v_add_f32_e32 v107, v96, v96
	v_cmp_nlt_f32_e32 vcc, s83, v107
	s_and_saveexec_b64 s[4:5], vcc
	s_xor_b64 s[4:5], exec, s[4:5]
	v_mul_f32_e32 v106, 0x3fb8aa3b, v107
	v_exp_f32_e32 v106, v106
	s_nop 0
	v_sub_f32_e32 v106, 1.0, v106
	s_andn2_saveexec_b64 s[4:5], s[4:5]
	v_fmamk_f32 v106, v107, 0x3c088889, v199
	v_fmaak_f32 v106, v107, v106, 0x3e2aaaab
	v_fma_f32 v106, v107, v106, 0.5
	v_fma_f32 v106, v107, v106, 1.0
	v_mul_f32_e64 v106, v106, -v107
	s_or_b64 exec, exec, s[4:5]
	v_add_f32_e32 v97, v97, v69
	v_mul_f32_e32 v97, 0xbfb8aa3b, v97
	v_exp_f32_e32 v97, v97
	s_nop 0
	v_add_f32_e32 v97, 1.0, v97
	v_rcp_f32_e32 v97, v97
	s_nop 0
	v_mul_f32_e32 v97, v97, v145
	v_add_f32_e32 v108, v97, v97
	v_cmp_nlt_f32_e32 vcc, s83, v108
	s_and_saveexec_b64 s[4:5], vcc
	s_xor_b64 s[4:5], exec, s[4:5]
	v_mul_f32_e32 v107, 0x3fb8aa3b, v108
	v_exp_f32_e32 v107, v107
	s_nop 0
	v_sub_f32_e32 v107, 1.0, v107
	s_andn2_saveexec_b64 s[4:5], s[4:5]
	v_fmamk_f32 v107, v108, 0x3c088889, v199
	v_fmaak_f32 v107, v108, v107, 0x3e2aaaab
	v_fma_f32 v107, v108, v107, 0.5
	v_fma_f32 v107, v108, v107, 1.0
	v_mul_f32_e64 v107, v107, -v108
	s_or_b64 exec, exec, s[4:5]
	v_add_f32_e32 v90, v90, v58
	v_mul_f32_e32 v90, 0xbfb8aa3b, v90
	v_exp_f32_e32 v90, v90
	s_nop 0
	v_add_f32_e32 v90, 1.0, v90
	v_rcp_f32_e32 v90, v90
	s_nop 0
	v_mul_f32_e32 v90, v90, v138
	v_add_f32_e32 v109, v90, v90
	v_cmp_nlt_f32_e32 vcc, s83, v109
	s_and_saveexec_b64 s[4:5], vcc
	s_xor_b64 s[4:5], exec, s[4:5]
	v_mul_f32_e32 v108, 0x3fb8aa3b, v109
	v_exp_f32_e32 v108, v108
	s_nop 0
	v_sub_f32_e32 v108, 1.0, v108
	s_andn2_saveexec_b64 s[4:5], s[4:5]
	v_fmamk_f32 v108, v109, 0x3c088889, v199
	v_fmaak_f32 v108, v109, v108, 0x3e2aaaab
	v_fma_f32 v108, v109, v108, 0.5
	v_fma_f32 v108, v109, v108, 1.0
	v_mul_f32_e64 v108, v108, -v109
	s_or_b64 exec, exec, s[4:5]
	v_add_f32_e32 v91, v91, v59
	v_mul_f32_e32 v91, 0xbfb8aa3b, v91
	v_exp_f32_e32 v91, v91
	s_nop 0
	v_add_f32_e32 v91, 1.0, v91
	v_rcp_f32_e32 v91, v91
	s_nop 0
	v_mul_f32_e32 v91, v91, v139
	v_add_f32_e32 v110, v91, v91
	v_cmp_nlt_f32_e32 vcc, s83, v110
	s_and_saveexec_b64 s[4:5], vcc
	s_xor_b64 s[4:5], exec, s[4:5]
	v_mul_f32_e32 v109, 0x3fb8aa3b, v110
	v_exp_f32_e32 v109, v109
	s_nop 0
	v_sub_f32_e32 v109, 1.0, v109
	s_andn2_saveexec_b64 s[4:5], s[4:5]
	v_fmamk_f32 v109, v110, 0x3c088889, v199
	v_fmaak_f32 v109, v110, v109, 0x3e2aaaab
	v_fma_f32 v109, v110, v109, 0.5
	v_fma_f32 v109, v110, v109, 1.0
	v_mul_f32_e64 v109, v109, -v110
	s_or_b64 exec, exec, s[4:5]
	v_add_f32_e32 v92, v92, v60
	v_mul_f32_e32 v92, 0xbfb8aa3b, v92
	v_exp_f32_e32 v92, v92
	s_nop 0
	v_add_f32_e32 v92, 1.0, v92
	v_rcp_f32_e32 v92, v92
	s_nop 0
	v_mul_f32_e32 v92, v92, v140
	v_add_f32_e32 v110, v92, v92
	v_cmp_nlt_f32_e32 vcc, s83, v110
	s_and_saveexec_b64 s[4:5], vcc
	s_xor_b64 s[4:5], exec, s[4:5]
	v_mul_f32_e32 v110, 0x3fb8aa3b, v110
	v_exp_f32_e32 v110, v110
	s_nop 0
	v_sub_f32_e32 v111, 1.0, v110
	s_andn2_saveexec_b64 s[4:5], s[4:5]
	v_fmamk_f32 v111, v110, 0x3c088889, v199
	v_fmaak_f32 v111, v110, v111, 0x3e2aaaab
	v_fma_f32 v111, v110, v111, 0.5
	v_fma_f32 v111, v110, v111, 1.0
	v_mul_f32_e64 v111, v111, -v110
	s_or_b64 exec, exec, s[4:5]
	v_add_f32_e32 v93, v93, v61
	v_mul_f32_e32 v93, 0xbfb8aa3b, v93
	v_exp_f32_e32 v93, v93
	s_nop 0
	v_add_f32_e32 v93, 1.0, v93
	v_rcp_f32_e32 v93, v93
	s_nop 0
	v_mul_f32_e32 v93, v93, v141
	v_add_f32_e32 v112, v93, v93
	v_cmp_nlt_f32_e32 vcc, s83, v112
	s_and_saveexec_b64 s[4:5], vcc
	s_xor_b64 s[4:5], exec, s[4:5]
	v_mul_f32_e32 v110, 0x3fb8aa3b, v112
	v_exp_f32_e32 v110, v110
	s_nop 0
	v_sub_f32_e32 v110, 1.0, v110
	s_andn2_saveexec_b64 s[4:5], s[4:5]
	v_fmamk_f32 v110, v112, 0x3c088889, v199
	v_fmaak_f32 v110, v112, v110, 0x3e2aaaab
	v_fma_f32 v110, v112, v110, 0.5
	v_fma_f32 v110, v112, v110, 1.0
	v_mul_f32_e64 v110, v110, -v112
	s_or_b64 exec, exec, s[4:5]
	v_add_f32_e32 v88, v88, v52
	v_mul_f32_e32 v88, 0xbfb8aa3b, v88
	v_exp_f32_e32 v88, v88
	v_add_f32_e32 v87, v87, v51
	v_mul_f32_e32 v87, 0xbfb8aa3b, v87
	v_add_f32_e32 v89, v89, v53
	v_add_f32_e32 v88, 1.0, v88
	v_exp_f32_e32 v87, v87
	v_rcp_f32_e32 v88, v88
	v_mul_f32_e32 v89, 0xbfb8aa3b, v89
	v_sqrt_f32_e32 v111, v111
	v_exp_f32_e32 v89, v89
	v_add_f32_e32 v86, v86, v50
	v_mul_f32_e32 v86, 0xbfb8aa3b, v86
	v_lshlrev_b32_e32 v112, 16, v101
	v_add_f32_e32 v87, 1.0, v87
	v_exp_f32_e32 v86, v86
	v_mul_f32_e32 v88, v88, v112
	v_rcp_f32_e32 v87, v87
	v_mul_f32_e32 v111, v88, v111
	v_add_f32_e32 v88, 1.0, v89
	v_sqrt_f32_e32 v89, v109
	v_add_f32_e32 v85, v85, v49
	v_mul_f32_e32 v85, 0xbfb8aa3b, v85
	v_and_b32_e32 v109, 0xffff0000, v100
	v_add_f32_e32 v86, 1.0, v86
	v_exp_f32_e32 v85, v85
	v_mul_f32_e32 v87, v87, v109
	v_rcp_f32_e32 v86, v86
	v_mul_f32_e32 v109, v87, v89
	v_sqrt_f32_e32 v87, v108
	v_add_f32_e32 v84, v84, v48
	v_mul_f32_e32 v84, 0xbfb8aa3b, v84
	v_lshlrev_b32_e32 v89, 16, v100
	v_add_f32_e32 v85, 1.0, v85
	v_exp_f32_e32 v84, v84
	v_mul_f32_e32 v86, v86, v89
	v_rcp_f32_e32 v85, v85
	v_mul_f32_e32 v100, v86, v87
	v_sqrt_f32_e32 v86, v107
	v_add_f32_e32 v83, v83, v47
	v_mul_f32_e32 v83, 0xbfb8aa3b, v83
	v_and_b32_e32 v87, 0xffff0000, v99
	v_add_f32_e32 v84, 1.0, v84
	v_exp_f32_e32 v83, v83
	v_mul_f32_e32 v85, v85, v87
	v_rcp_f32_e32 v84, v84
	v_add_f32_e32 v82, v82, v46
	v_mul_f32_e32 v107, v85, v86
	v_sqrt_f32_e32 v85, v106
	v_mul_f32_e32 v82, 0xbfb8aa3b, v82
	v_exp_f32_e32 v82, v82
	v_lshlrev_b32_e32 v86, 16, v99
	v_add_f32_e32 v83, 1.0, v83
	v_mul_f32_e32 v84, v84, v86
	v_rcp_f32_e32 v83, v83
	v_mul_f32_e32 v99, v84, v85
	v_sqrt_f32_e32 v85, v105
	v_add_f32_e32 v82, 1.0, v82
	v_and_b32_e32 v84, 0xffff0000, v98
	v_rcp_f32_e32 v82, v82
	v_mul_f32_e32 v83, v83, v84
	v_mul_f32_e32 v105, v83, v85
	v_sqrt_f32_e32 v83, v104
	v_rcp_f32_e32 v88, v88
	v_lshlrev_b32_e32 v84, 16, v98
	v_mul_f32_e32 v82, v82, v84
	v_sqrt_f32_e32 v84, v110
	v_mul_f32_e32 v98, v82, v83
	v_and_b32_e32 v82, 0xffff0000, v101
	v_mul_f32_e32 v82, v88, v82
	v_lshlrev_b64 v[86:87], 1, v[102:103]
	v_mul_f32_e32 v101, v82, v84
	v_lshl_add_u64 v[88:89], s[20:21], 0, v[86:87]
	v_cvt_pk_bf16_f32 v82, v94, v95
	v_cvt_pk_bf16_f32 v83, v96, v97
	v_cvt_pk_bf16_f32 v84, v90, v91
	v_cvt_pk_bf16_f32 v85, v92, v93
	global_store_dwordx4 v[88:89], v[82:85], off
	v_lshl_add_u64 v[86:87], s[22:23], 0, v[86:87]
	v_add_f32_e32 v78, v78, v66
	v_cvt_pk_bf16_f32 v82, v98, v105
	v_cvt_pk_bf16_f32 v83, v99, v107
	v_cvt_pk_bf16_f32 v84, v100, v109
	v_cvt_pk_bf16_f32 v85, v111, v101
	global_store_dwordx4 v[86:87], v[82:85], off
	v_mul_f32_e32 v78, 0xbfb8aa3b, v78
	v_exp_f32_e32 v78, v78
	v_add_u32_e32 v82, 0x80, v0
	v_mov_b32_e32 v83, v1
	v_lshlrev_b64 v[82:83], 11, v[82:83]
	v_lshl_add_u64 v[86:87], v[82:83], 0, v[170:171]
	v_lshl_add_u64 v[82:83], v[86:87], 1, s[0:1]
	v_mov_b32_e32 v82, v218
	v_mov_b32_e32 v83, v219
	v_mov_b32_e32 v84, v220
	v_mov_b32_e32 v85, v221
	v_add_f32_e32 v78, 1.0, v78
	v_rcp_f32_e32 v78, v78
	s_nop 0
	v_mul_f32_e32 v78, v78, v142
	v_add_f32_e32 v89, v78, v78
	v_cmp_nlt_f32_e32 vcc, s83, v89
	s_and_saveexec_b64 s[4:5], vcc
	s_xor_b64 s[4:5], exec, s[4:5]
	v_mul_f32_e32 v88, 0x3fb8aa3b, v89
	v_exp_f32_e32 v88, v88
	s_nop 0
	v_sub_f32_e32 v88, 1.0, v88
	s_andn2_saveexec_b64 s[4:5], s[4:5]
	v_fmamk_f32 v88, v89, 0x3c088889, v199
	v_fmaak_f32 v88, v89, v88, 0x3e2aaaab
	v_fma_f32 v88, v89, v88, 0.5
	v_fma_f32 v88, v89, v88, 1.0
	v_mul_f32_e64 v88, v88, -v89
	s_or_b64 exec, exec, s[4:5]
	v_add_f32_e32 v79, v79, v67
	v_mul_f32_e32 v79, 0xbfb8aa3b, v79
	v_exp_f32_e32 v79, v79
	s_nop 0
	v_add_f32_e32 v79, 1.0, v79
	v_rcp_f32_e32 v79, v79
	s_nop 0
	v_mul_f32_e32 v79, v79, v143
	v_add_f32_e32 v90, v79, v79
	v_cmp_nlt_f32_e32 vcc, s83, v90
	s_and_saveexec_b64 s[4:5], vcc
	s_xor_b64 s[4:5], exec, s[4:5]
	v_mul_f32_e32 v89, 0x3fb8aa3b, v90
	v_exp_f32_e32 v89, v89
	s_nop 0
	v_sub_f32_e32 v89, 1.0, v89
	s_andn2_saveexec_b64 s[4:5], s[4:5]
	v_fmamk_f32 v89, v90, 0x3c088889, v199
	v_fmaak_f32 v89, v90, v89, 0x3e2aaaab
	v_fma_f32 v89, v90, v89, 0.5
	v_fma_f32 v89, v90, v89, 1.0
	v_mul_f32_e64 v89, v89, -v90
	s_or_b64 exec, exec, s[4:5]
	v_add_f32_e32 v80, v80, v68
	v_mul_f32_e32 v80, 0xbfb8aa3b, v80
	v_exp_f32_e32 v80, v80
	s_nop 0
	v_add_f32_e32 v80, 1.0, v80
	v_rcp_f32_e32 v80, v80
	s_nop 0
	v_mul_f32_e32 v80, v80, v144
	v_add_f32_e32 v91, v80, v80
	v_cmp_nlt_f32_e32 vcc, s83, v91
	s_and_saveexec_b64 s[4:5], vcc
	s_xor_b64 s[4:5], exec, s[4:5]
	v_mul_f32_e32 v90, 0x3fb8aa3b, v91
	v_exp_f32_e32 v90, v90
	s_nop 0
	v_sub_f32_e32 v90, 1.0, v90
	s_andn2_saveexec_b64 s[4:5], s[4:5]
	v_fmamk_f32 v90, v91, 0x3c088889, v199
	v_fmaak_f32 v90, v91, v90, 0x3e2aaaab
	v_fma_f32 v90, v91, v90, 0.5
	v_fma_f32 v90, v91, v90, 1.0
	v_mul_f32_e64 v90, v90, -v91
	s_or_b64 exec, exec, s[4:5]
	v_add_f32_e32 v81, v81, v69
	v_mul_f32_e32 v81, 0xbfb8aa3b, v81
	v_exp_f32_e32 v81, v81
	s_nop 0
	v_add_f32_e32 v81, 1.0, v81
	v_rcp_f32_e32 v81, v81
	s_nop 0
	v_mul_f32_e32 v81, v81, v145
	v_add_f32_e32 v92, v81, v81
	v_cmp_nlt_f32_e32 vcc, s83, v92
	s_and_saveexec_b64 s[4:5], vcc
	s_xor_b64 s[4:5], exec, s[4:5]
	v_mul_f32_e32 v91, 0x3fb8aa3b, v92
	v_exp_f32_e32 v91, v91
	s_nop 0
	v_sub_f32_e32 v91, 1.0, v91
	s_andn2_saveexec_b64 s[4:5], s[4:5]
	v_fmamk_f32 v91, v92, 0x3c088889, v199
	v_fmaak_f32 v91, v92, v91, 0x3e2aaaab
	v_fma_f32 v91, v92, v91, 0.5
	v_fma_f32 v91, v92, v91, 1.0
	v_mul_f32_e64 v91, v91, -v92
	s_or_b64 exec, exec, s[4:5]
	v_add_f32_e32 v74, v74, v58
	v_mul_f32_e32 v74, 0xbfb8aa3b, v74
	v_exp_f32_e32 v74, v74
	s_nop 0
	v_add_f32_e32 v74, 1.0, v74
	v_rcp_f32_e32 v74, v74
	s_nop 0
	v_mul_f32_e32 v74, v74, v138
	v_add_f32_e32 v93, v74, v74
	v_cmp_nlt_f32_e32 vcc, s83, v93
	s_and_saveexec_b64 s[4:5], vcc
	s_xor_b64 s[4:5], exec, s[4:5]
	v_mul_f32_e32 v92, 0x3fb8aa3b, v93
	v_exp_f32_e32 v92, v92
	s_nop 0
	v_sub_f32_e32 v92, 1.0, v92
	s_andn2_saveexec_b64 s[4:5], s[4:5]
	v_fmamk_f32 v92, v93, 0x3c088889, v199
	v_fmaak_f32 v92, v93, v92, 0x3e2aaaab
	v_fma_f32 v92, v93, v92, 0.5
	v_fma_f32 v92, v93, v92, 1.0
	v_mul_f32_e64 v92, v92, -v93
	s_or_b64 exec, exec, s[4:5]
	v_add_f32_e32 v75, v75, v59
	v_mul_f32_e32 v75, 0xbfb8aa3b, v75
	v_exp_f32_e32 v75, v75
	s_nop 0
	v_add_f32_e32 v75, 1.0, v75
	v_rcp_f32_e32 v75, v75
	s_nop 0
	v_mul_f32_e32 v75, v75, v139
	v_add_f32_e32 v94, v75, v75
	v_cmp_nlt_f32_e32 vcc, s83, v94
	s_and_saveexec_b64 s[4:5], vcc
	s_xor_b64 s[4:5], exec, s[4:5]
	v_mul_f32_e32 v93, 0x3fb8aa3b, v94
	v_exp_f32_e32 v93, v93
	s_nop 0
	v_sub_f32_e32 v93, 1.0, v93
	s_andn2_saveexec_b64 s[4:5], s[4:5]
	v_fmamk_f32 v93, v94, 0x3c088889, v199
	v_fmaak_f32 v93, v94, v93, 0x3e2aaaab
	v_fma_f32 v93, v94, v93, 0.5
	v_fma_f32 v93, v94, v93, 1.0
	v_mul_f32_e64 v93, v93, -v94
	s_or_b64 exec, exec, s[4:5]
	v_add_f32_e32 v76, v76, v60
	v_mul_f32_e32 v76, 0xbfb8aa3b, v76
	v_exp_f32_e32 v76, v76
	s_nop 0
	v_add_f32_e32 v76, 1.0, v76
	v_rcp_f32_e32 v76, v76
	s_nop 0
	v_mul_f32_e32 v76, v76, v140
	v_add_f32_e32 v94, v76, v76
	v_cmp_nlt_f32_e32 vcc, s83, v94
	s_and_saveexec_b64 s[4:5], vcc
	s_xor_b64 s[4:5], exec, s[4:5]
	v_mul_f32_e32 v94, 0x3fb8aa3b, v94
	v_exp_f32_e32 v94, v94
	s_nop 0
	v_sub_f32_e32 v95, 1.0, v94
	s_andn2_saveexec_b64 s[4:5], s[4:5]
	v_fmamk_f32 v95, v94, 0x3c088889, v199
	v_fmaak_f32 v95, v94, v95, 0x3e2aaaab
	v_fma_f32 v95, v94, v95, 0.5
	v_fma_f32 v95, v94, v95, 1.0
	v_mul_f32_e64 v95, v95, -v94
	s_or_b64 exec, exec, s[4:5]
	v_add_f32_e32 v77, v77, v61
	v_mul_f32_e32 v77, 0xbfb8aa3b, v77
	v_exp_f32_e32 v77, v77
	s_nop 0
	v_add_f32_e32 v77, 1.0, v77
	v_rcp_f32_e32 v77, v77
	s_nop 0
	v_mul_f32_e32 v77, v77, v141
	v_add_f32_e32 v96, v77, v77
	v_cmp_nlt_f32_e32 vcc, s83, v96
	s_and_saveexec_b64 s[4:5], vcc
	s_xor_b64 s[4:5], exec, s[4:5]
	v_mul_f32_e32 v94, 0x3fb8aa3b, v96
	v_exp_f32_e32 v94, v94
	s_nop 0
	v_sub_f32_e32 v94, 1.0, v94
	s_andn2_saveexec_b64 s[4:5], s[4:5]
	v_fmamk_f32 v94, v96, 0x3c088889, v199
	v_fmaak_f32 v94, v96, v94, 0x3e2aaaab
	v_fma_f32 v94, v96, v94, 0.5
	v_fma_f32 v94, v96, v94, 1.0
	v_mul_f32_e64 v94, v94, -v96
	s_or_b64 exec, exec, s[4:5]
	v_add_f32_e32 v72, v72, v52
	v_mul_f32_e32 v72, 0xbfb8aa3b, v72
	v_exp_f32_e32 v72, v72
	v_add_f32_e32 v71, v71, v51
	v_mul_f32_e32 v71, 0xbfb8aa3b, v71
	v_add_f32_e32 v73, v73, v53
	v_add_f32_e32 v72, 1.0, v72
	v_exp_f32_e32 v71, v71
	v_rcp_f32_e32 v72, v72
	v_mul_f32_e32 v73, 0xbfb8aa3b, v73
	v_sqrt_f32_e32 v95, v95
	v_exp_f32_e32 v73, v73
	v_add_f32_e32 v70, v70, v50
	v_mul_f32_e32 v70, 0xbfb8aa3b, v70
	v_lshlrev_b32_e32 v96, 16, v85
	v_add_f32_e32 v71, 1.0, v71
	v_exp_f32_e32 v70, v70
	v_mul_f32_e32 v72, v72, v96
	v_rcp_f32_e32 v71, v71
	v_mul_f32_e32 v95, v72, v95
	v_add_f32_e32 v72, 1.0, v73
	v_sqrt_f32_e32 v73, v93
	v_add_f32_e32 v65, v65, v49
	v_mul_f32_e32 v65, 0xbfb8aa3b, v65
	v_and_b32_e32 v93, 0xffff0000, v84
	v_add_f32_e32 v70, 1.0, v70
	v_exp_f32_e32 v65, v65
	v_mul_f32_e32 v71, v71, v93
	v_rcp_f32_e32 v70, v70
	v_mul_f32_e32 v93, v71, v73
	v_sqrt_f32_e32 v71, v92
	v_add_f32_e32 v64, v64, v48
	v_mul_f32_e32 v64, 0xbfb8aa3b, v64
	v_lshlrev_b32_e32 v73, 16, v84
	v_add_f32_e32 v65, 1.0, v65
	v_exp_f32_e32 v64, v64
	v_mul_f32_e32 v70, v70, v73
	v_rcp_f32_e32 v65, v65
	v_mul_f32_e32 v84, v70, v71
	v_sqrt_f32_e32 v70, v91
	v_add_f32_e32 v63, v63, v47
	v_mul_f32_e32 v63, 0xbfb8aa3b, v63
	v_and_b32_e32 v71, 0xffff0000, v83
	v_add_f32_e32 v64, 1.0, v64
	v_exp_f32_e32 v63, v63
	v_mul_f32_e32 v65, v65, v71
	v_rcp_f32_e32 v64, v64
	v_add_f32_e32 v62, v62, v46
	v_mul_f32_e32 v91, v65, v70
	v_sqrt_f32_e32 v65, v90
	v_mul_f32_e32 v62, 0xbfb8aa3b, v62
	v_exp_f32_e32 v62, v62
	v_lshlrev_b32_e32 v70, 16, v83
	v_add_f32_e32 v63, 1.0, v63
	v_mul_f32_e32 v64, v64, v70
	v_rcp_f32_e32 v63, v63
	v_mul_f32_e32 v83, v64, v65
	v_sqrt_f32_e32 v65, v89
	v_add_f32_e32 v62, 1.0, v62
	v_and_b32_e32 v64, 0xffff0000, v82
	v_rcp_f32_e32 v62, v62
	v_mul_f32_e32 v63, v63, v64
	v_mul_f32_e32 v89, v63, v65
	v_sqrt_f32_e32 v63, v88
	v_rcp_f32_e32 v72, v72
	v_lshlrev_b32_e32 v64, 16, v82
	v_mul_f32_e32 v62, v62, v64
	v_sqrt_f32_e32 v64, v94
	v_mul_f32_e32 v82, v62, v63
	v_and_b32_e32 v62, 0xffff0000, v85
	v_mul_f32_e32 v62, v72, v62
	v_lshlrev_b64 v[70:71], 1, v[86:87]
	v_mul_f32_e32 v85, v62, v64
	v_lshl_add_u64 v[72:73], s[20:21], 0, v[70:71]
	v_cvt_pk_bf16_f32 v62, v78, v79
	v_cvt_pk_bf16_f32 v63, v80, v81
	v_cvt_pk_bf16_f32 v64, v74, v75
	v_cvt_pk_bf16_f32 v65, v76, v77
	global_store_dwordx4 v[72:73], v[62:65], off
	v_lshl_add_u64 v[70:71], s[22:23], 0, v[70:71]
	v_add_f32_e32 v54, v54, v66
	v_cvt_pk_bf16_f32 v62, v82, v89
	v_cvt_pk_bf16_f32 v63, v83, v91
	v_cvt_pk_bf16_f32 v64, v84, v93
	v_cvt_pk_bf16_f32 v65, v95, v85
	global_store_dwordx4 v[70:71], v[62:65], off
	v_mul_f32_e32 v54, 0xbfb8aa3b, v54
	v_exp_f32_e32 v54, v54
	v_add_u32_e32 v62, 0x90, v0
	v_mov_b32_e32 v63, v1
	v_lshlrev_b64 v[62:63], 11, v[62:63]
	v_lshl_add_u64 v[70:71], v[62:63], 0, v[170:171]
	v_lshl_add_u64 v[62:63], v[70:71], 1, s[0:1]
	v_mov_b32_e32 v62, v222
	v_mov_b32_e32 v63, v223
	v_mov_b32_e32 v64, v224
	v_mov_b32_e32 v65, v225
	v_add_f32_e32 v54, 1.0, v54
	v_rcp_f32_e32 v54, v54
	s_nop 0
	v_mul_f32_e32 v54, v54, v142
	v_add_f32_e32 v73, v54, v54
	v_cmp_nlt_f32_e32 vcc, s83, v73
	s_and_saveexec_b64 s[4:5], vcc
	s_xor_b64 s[4:5], exec, s[4:5]
	v_mul_f32_e32 v72, 0x3fb8aa3b, v73
	v_exp_f32_e32 v72, v72
	s_nop 0
	v_sub_f32_e32 v72, 1.0, v72
	s_andn2_saveexec_b64 s[4:5], s[4:5]
	v_fmamk_f32 v72, v73, 0x3c088889, v199
	v_fmaak_f32 v72, v73, v72, 0x3e2aaaab
	v_fma_f32 v72, v73, v72, 0.5
	v_fma_f32 v72, v73, v72, 1.0
	v_mul_f32_e64 v72, v72, -v73
	s_or_b64 exec, exec, s[4:5]
	v_add_f32_e32 v55, v55, v67
	v_mul_f32_e32 v55, 0xbfb8aa3b, v55
	v_exp_f32_e32 v55, v55
	s_nop 0
	v_add_f32_e32 v55, 1.0, v55
	v_rcp_f32_e32 v55, v55
	s_nop 0
	v_mul_f32_e32 v55, v55, v143
	v_add_f32_e32 v74, v55, v55
	v_cmp_nlt_f32_e32 vcc, s83, v74
	s_and_saveexec_b64 s[4:5], vcc
	s_xor_b64 s[4:5], exec, s[4:5]
	v_mul_f32_e32 v73, 0x3fb8aa3b, v74
	v_exp_f32_e32 v73, v73
	s_nop 0
	v_sub_f32_e32 v73, 1.0, v73
	s_andn2_saveexec_b64 s[4:5], s[4:5]
	v_fmamk_f32 v73, v74, 0x3c088889, v199
	v_fmaak_f32 v73, v74, v73, 0x3e2aaaab
	v_fma_f32 v73, v74, v73, 0.5
	v_fma_f32 v73, v74, v73, 1.0
	v_mul_f32_e64 v73, v73, -v74
	s_or_b64 exec, exec, s[4:5]
	v_add_f32_e32 v56, v56, v68
	v_mul_f32_e32 v56, 0xbfb8aa3b, v56
	v_exp_f32_e32 v56, v56
	s_nop 0
	v_add_f32_e32 v56, 1.0, v56
	v_rcp_f32_e32 v56, v56
	s_nop 0
	v_mul_f32_e32 v56, v56, v144
	v_add_f32_e32 v75, v56, v56
	v_cmp_nlt_f32_e32 vcc, s83, v75
	s_and_saveexec_b64 s[4:5], vcc
	s_xor_b64 s[4:5], exec, s[4:5]
	v_mul_f32_e32 v74, 0x3fb8aa3b, v75
	v_exp_f32_e32 v74, v74
	s_nop 0
	v_sub_f32_e32 v74, 1.0, v74
	s_andn2_saveexec_b64 s[4:5], s[4:5]
	v_fmamk_f32 v74, v75, 0x3c088889, v199
	v_fmaak_f32 v74, v75, v74, 0x3e2aaaab
	v_fma_f32 v74, v75, v74, 0.5
	v_fma_f32 v74, v75, v74, 1.0
	v_mul_f32_e64 v74, v74, -v75
	s_or_b64 exec, exec, s[4:5]
	v_add_f32_e32 v57, v57, v69
	v_mul_f32_e32 v57, 0xbfb8aa3b, v57
	v_exp_f32_e32 v57, v57
	s_nop 0
	v_add_f32_e32 v57, 1.0, v57
	v_rcp_f32_e32 v57, v57
	s_nop 0
	v_mul_f32_e32 v57, v57, v145
	v_add_f32_e32 v76, v57, v57
	v_cmp_nlt_f32_e32 vcc, s83, v76
	s_and_saveexec_b64 s[4:5], vcc
	s_xor_b64 s[4:5], exec, s[4:5]
	v_mul_f32_e32 v75, 0x3fb8aa3b, v76
	v_exp_f32_e32 v75, v75
	s_nop 0
	v_sub_f32_e32 v75, 1.0, v75
	s_andn2_saveexec_b64 s[4:5], s[4:5]
	v_fmamk_f32 v75, v76, 0x3c088889, v199
	v_fmaak_f32 v75, v76, v75, 0x3e2aaaab
	v_fma_f32 v75, v76, v75, 0.5
	v_fma_f32 v75, v76, v75, 1.0
	v_mul_f32_e64 v75, v75, -v76
	s_or_b64 exec, exec, s[4:5]
	v_add_f32_e32 v42, v42, v58
	v_mul_f32_e32 v42, 0xbfb8aa3b, v42
	v_exp_f32_e32 v42, v42
	s_nop 0
	v_add_f32_e32 v42, 1.0, v42
	v_rcp_f32_e32 v42, v42
	s_nop 0
	v_mul_f32_e32 v42, v42, v138
	v_add_f32_e32 v77, v42, v42
	v_cmp_nlt_f32_e32 vcc, s83, v77
	s_and_saveexec_b64 s[4:5], vcc
	s_xor_b64 s[4:5], exec, s[4:5]
	v_mul_f32_e32 v76, 0x3fb8aa3b, v77
	v_exp_f32_e32 v76, v76
	s_nop 0
	v_sub_f32_e32 v76, 1.0, v76
	s_andn2_saveexec_b64 s[4:5], s[4:5]
	v_fmamk_f32 v76, v77, 0x3c088889, v199
	v_fmaak_f32 v76, v77, v76, 0x3e2aaaab
	v_fma_f32 v76, v77, v76, 0.5
	v_fma_f32 v76, v77, v76, 1.0
	v_mul_f32_e64 v76, v76, -v77
	s_or_b64 exec, exec, s[4:5]
	v_add_f32_e32 v43, v43, v59
	v_mul_f32_e32 v43, 0xbfb8aa3b, v43
	v_exp_f32_e32 v43, v43
	s_nop 0
	v_add_f32_e32 v43, 1.0, v43
	v_rcp_f32_e32 v43, v43
	s_nop 0
	v_mul_f32_e32 v43, v43, v139
	v_add_f32_e32 v78, v43, v43
	v_cmp_nlt_f32_e32 vcc, s83, v78
	s_and_saveexec_b64 s[4:5], vcc
	s_xor_b64 s[4:5], exec, s[4:5]
	v_mul_f32_e32 v77, 0x3fb8aa3b, v78
	v_exp_f32_e32 v77, v77
	s_nop 0
	v_sub_f32_e32 v77, 1.0, v77
	s_andn2_saveexec_b64 s[4:5], s[4:5]
	v_fmamk_f32 v77, v78, 0x3c088889, v199
	v_fmaak_f32 v77, v78, v77, 0x3e2aaaab
	v_fma_f32 v77, v78, v77, 0.5
	v_fma_f32 v77, v78, v77, 1.0
	v_mul_f32_e64 v77, v77, -v78
	s_or_b64 exec, exec, s[4:5]
	v_add_f32_e32 v44, v44, v60
	v_mul_f32_e32 v44, 0xbfb8aa3b, v44
	v_exp_f32_e32 v44, v44
	s_nop 0
	v_add_f32_e32 v44, 1.0, v44
	v_rcp_f32_e32 v44, v44
	s_nop 0
	v_mul_f32_e32 v44, v44, v140
	v_add_f32_e32 v78, v44, v44
	v_cmp_nlt_f32_e32 vcc, s83, v78
	s_and_saveexec_b64 s[4:5], vcc
	s_xor_b64 s[4:5], exec, s[4:5]
	v_mul_f32_e32 v78, 0x3fb8aa3b, v78
	v_exp_f32_e32 v78, v78
	s_nop 0
	v_sub_f32_e32 v79, 1.0, v78
	s_andn2_saveexec_b64 s[4:5], s[4:5]
	v_fmamk_f32 v79, v78, 0x3c088889, v199
	v_fmaak_f32 v79, v78, v79, 0x3e2aaaab
	v_fma_f32 v79, v78, v79, 0.5
	v_fma_f32 v79, v78, v79, 1.0
	v_mul_f32_e64 v79, v79, -v78
	s_or_b64 exec, exec, s[4:5]
	v_add_f32_e32 v45, v45, v61
	v_mul_f32_e32 v45, 0xbfb8aa3b, v45
	v_exp_f32_e32 v45, v45
	s_nop 0
	v_add_f32_e32 v45, 1.0, v45
	v_rcp_f32_e32 v45, v45
	s_nop 0
	v_mul_f32_e32 v45, v45, v141
	v_add_f32_e32 v80, v45, v45
	v_cmp_nlt_f32_e32 vcc, s83, v80
	s_and_saveexec_b64 s[4:5], vcc
	s_xor_b64 s[4:5], exec, s[4:5]
	v_mul_f32_e32 v78, 0x3fb8aa3b, v80
	v_exp_f32_e32 v78, v78
	s_nop 0
	v_sub_f32_e32 v78, 1.0, v78
	s_andn2_saveexec_b64 s[4:5], s[4:5]
	v_fmamk_f32 v78, v80, 0x3c088889, v199
	v_fmaak_f32 v78, v80, v78, 0x3e2aaaab
	v_fma_f32 v78, v80, v78, 0.5
	v_fma_f32 v78, v80, v78, 1.0
	v_mul_f32_e64 v78, v78, -v80
	s_or_b64 exec, exec, s[4:5]
	v_add_f32_e32 v40, v40, v52
	v_mul_f32_e32 v40, 0xbfb8aa3b, v40
	v_exp_f32_e32 v40, v40
	v_add_f32_e32 v39, v39, v51
	v_mul_f32_e32 v39, 0xbfb8aa3b, v39
	v_add_f32_e32 v41, v41, v53
	v_add_f32_e32 v40, 1.0, v40
	v_exp_f32_e32 v39, v39
	v_rcp_f32_e32 v40, v40
	v_mul_f32_e32 v41, 0xbfb8aa3b, v41
	v_sqrt_f32_e32 v79, v79
	v_exp_f32_e32 v41, v41
	v_add_f32_e32 v38, v38, v50
	v_mul_f32_e32 v38, 0xbfb8aa3b, v38
	v_lshlrev_b32_e32 v80, 16, v65
	v_add_f32_e32 v39, 1.0, v39
	v_exp_f32_e32 v38, v38
	v_mul_f32_e32 v40, v40, v80
	v_rcp_f32_e32 v39, v39
	v_mul_f32_e32 v79, v40, v79
	v_add_f32_e32 v40, 1.0, v41
	v_sqrt_f32_e32 v41, v77
	v_add_f32_e32 v37, v37, v49
	v_mul_f32_e32 v37, 0xbfb8aa3b, v37
	v_and_b32_e32 v77, 0xffff0000, v64
	v_add_f32_e32 v38, 1.0, v38
	v_exp_f32_e32 v37, v37
	v_mul_f32_e32 v39, v39, v77
	v_rcp_f32_e32 v38, v38
	v_mul_f32_e32 v77, v39, v41
	v_sqrt_f32_e32 v39, v76
	v_add_f32_e32 v36, v36, v48
	v_mul_f32_e32 v36, 0xbfb8aa3b, v36
	v_lshlrev_b32_e32 v41, 16, v64
	v_add_f32_e32 v37, 1.0, v37
	v_exp_f32_e32 v36, v36
	v_mul_f32_e32 v38, v38, v41
	v_rcp_f32_e32 v37, v37
	v_mul_f32_e32 v64, v38, v39
	v_sqrt_f32_e32 v38, v75
	v_add_f32_e32 v35, v35, v47
	v_mul_f32_e32 v35, 0xbfb8aa3b, v35
	v_and_b32_e32 v39, 0xffff0000, v63
	v_add_f32_e32 v36, 1.0, v36
	v_exp_f32_e32 v35, v35
	v_mul_f32_e32 v37, v37, v39
	v_rcp_f32_e32 v36, v36
	v_add_f32_e32 v34, v34, v46
	v_mul_f32_e32 v75, v37, v38
	v_sqrt_f32_e32 v37, v74
	v_mul_f32_e32 v34, 0xbfb8aa3b, v34
	v_exp_f32_e32 v34, v34
	v_lshlrev_b32_e32 v38, 16, v63
	v_add_f32_e32 v35, 1.0, v35
	v_mul_f32_e32 v36, v36, v38
	v_rcp_f32_e32 v35, v35
	v_mul_f32_e32 v63, v36, v37
	v_sqrt_f32_e32 v37, v73
	v_add_f32_e32 v34, 1.0, v34
	v_and_b32_e32 v36, 0xffff0000, v62
	v_rcp_f32_e32 v34, v34
	v_mul_f32_e32 v35, v35, v36
	v_mul_f32_e32 v73, v35, v37
	v_sqrt_f32_e32 v35, v72
	v_rcp_f32_e32 v40, v40
	v_lshlrev_b32_e32 v36, 16, v62
	v_mul_f32_e32 v34, v34, v36
	v_sqrt_f32_e32 v36, v78
	v_mul_f32_e32 v62, v34, v35
	v_and_b32_e32 v34, 0xffff0000, v65
	v_mul_f32_e32 v34, v40, v34
	v_lshlrev_b64 v[38:39], 1, v[70:71]
	v_mul_f32_e32 v65, v34, v36
	v_lshl_add_u64 v[40:41], s[20:21], 0, v[38:39]
	v_cvt_pk_bf16_f32 v34, v54, v55
	v_cvt_pk_bf16_f32 v35, v56, v57
	v_cvt_pk_bf16_f32 v36, v42, v43
	v_cvt_pk_bf16_f32 v37, v44, v45
	global_store_dwordx4 v[40:41], v[34:37], off
	v_lshl_add_u64 v[38:39], s[22:23], 0, v[38:39]
	v_add_f32_e32 v30, v30, v66
	v_cvt_pk_bf16_f32 v34, v62, v73
	v_cvt_pk_bf16_f32 v35, v63, v75
	v_cvt_pk_bf16_f32 v36, v64, v77
	v_cvt_pk_bf16_f32 v37, v79, v65
	global_store_dwordx4 v[38:39], v[34:37], off
	v_mul_f32_e32 v30, 0xbfb8aa3b, v30
	v_exp_f32_e32 v30, v30
	v_add_u32_e32 v34, 0xa0, v0
	v_mov_b32_e32 v35, v1
	v_lshlrev_b64 v[34:35], 11, v[34:35]
	v_lshl_add_u64 v[38:39], v[34:35], 0, v[170:171]
	v_lshl_add_u64 v[34:35], v[38:39], 1, s[0:1]
	v_mov_b32_e32 v34, v226
	v_mov_b32_e32 v35, v227
	v_mov_b32_e32 v36, v228
	v_mov_b32_e32 v37, v229
	v_add_f32_e32 v30, 1.0, v30
	v_rcp_f32_e32 v30, v30
	s_nop 0
	v_mul_f32_e32 v30, v30, v142
	v_add_f32_e32 v41, v30, v30
	v_cmp_nlt_f32_e32 vcc, s83, v41
	s_and_saveexec_b64 s[4:5], vcc
	s_xor_b64 s[4:5], exec, s[4:5]
	v_mul_f32_e32 v40, 0x3fb8aa3b, v41
	v_exp_f32_e32 v40, v40
	s_nop 0
	v_sub_f32_e32 v40, 1.0, v40
	s_andn2_saveexec_b64 s[4:5], s[4:5]
	v_fmamk_f32 v40, v41, 0x3c088889, v199
	v_fmaak_f32 v40, v41, v40, 0x3e2aaaab
	v_fma_f32 v40, v41, v40, 0.5
	v_fma_f32 v40, v41, v40, 1.0
	v_mul_f32_e64 v40, v40, -v41
	s_or_b64 exec, exec, s[4:5]
	v_add_f32_e32 v31, v31, v67
	v_mul_f32_e32 v31, 0xbfb8aa3b, v31
	v_exp_f32_e32 v31, v31
	s_nop 0
	v_add_f32_e32 v31, 1.0, v31
	v_rcp_f32_e32 v31, v31
	s_nop 0
	v_mul_f32_e32 v31, v31, v143
	v_add_f32_e32 v42, v31, v31
	v_cmp_nlt_f32_e32 vcc, s83, v42
	s_and_saveexec_b64 s[4:5], vcc
	s_xor_b64 s[4:5], exec, s[4:5]
	v_mul_f32_e32 v41, 0x3fb8aa3b, v42
	v_exp_f32_e32 v41, v41
	s_nop 0
	v_sub_f32_e32 v41, 1.0, v41
	s_andn2_saveexec_b64 s[4:5], s[4:5]
	v_fmamk_f32 v41, v42, 0x3c088889, v199
	v_fmaak_f32 v41, v42, v41, 0x3e2aaaab
	v_fma_f32 v41, v42, v41, 0.5
	v_fma_f32 v41, v42, v41, 1.0
	v_mul_f32_e64 v41, v41, -v42
	s_or_b64 exec, exec, s[4:5]
	v_add_f32_e32 v32, v32, v68
	v_mul_f32_e32 v32, 0xbfb8aa3b, v32
	v_exp_f32_e32 v32, v32
	s_nop 0
	v_add_f32_e32 v32, 1.0, v32
	v_rcp_f32_e32 v32, v32
	s_nop 0
	v_mul_f32_e32 v32, v32, v144
	v_add_f32_e32 v43, v32, v32
	v_cmp_nlt_f32_e32 vcc, s83, v43
	s_and_saveexec_b64 s[4:5], vcc
	s_xor_b64 s[4:5], exec, s[4:5]
	v_mul_f32_e32 v42, 0x3fb8aa3b, v43
	v_exp_f32_e32 v42, v42
	s_nop 0
	v_sub_f32_e32 v42, 1.0, v42
	s_andn2_saveexec_b64 s[4:5], s[4:5]
	v_fmamk_f32 v42, v43, 0x3c088889, v199
	v_fmaak_f32 v42, v43, v42, 0x3e2aaaab
	v_fma_f32 v42, v43, v42, 0.5
	v_fma_f32 v42, v43, v42, 1.0
	v_mul_f32_e64 v42, v42, -v43
	s_or_b64 exec, exec, s[4:5]
	v_add_f32_e32 v33, v33, v69
	v_mul_f32_e32 v33, 0xbfb8aa3b, v33
	v_exp_f32_e32 v33, v33
	s_nop 0
	v_add_f32_e32 v33, 1.0, v33
	v_rcp_f32_e32 v33, v33
	s_nop 0
	v_mul_f32_e32 v33, v33, v145
	v_add_f32_e32 v44, v33, v33
	v_cmp_nlt_f32_e32 vcc, s83, v44
	s_and_saveexec_b64 s[4:5], vcc
	s_xor_b64 s[4:5], exec, s[4:5]
	v_mul_f32_e32 v43, 0x3fb8aa3b, v44
	v_exp_f32_e32 v43, v43
	s_nop 0
	v_sub_f32_e32 v43, 1.0, v43
	s_andn2_saveexec_b64 s[4:5], s[4:5]
	v_fmamk_f32 v43, v44, 0x3c088889, v199
	v_fmaak_f32 v43, v44, v43, 0x3e2aaaab
	v_fma_f32 v43, v44, v43, 0.5
	v_fma_f32 v43, v44, v43, 1.0
	v_mul_f32_e64 v43, v43, -v44
	s_or_b64 exec, exec, s[4:5]
	v_add_f32_e32 v26, v26, v58
	v_mul_f32_e32 v26, 0xbfb8aa3b, v26
	v_exp_f32_e32 v26, v26
	s_nop 0
	v_add_f32_e32 v26, 1.0, v26
	v_rcp_f32_e32 v26, v26
	s_nop 0
	v_mul_f32_e32 v26, v26, v138
	v_add_f32_e32 v45, v26, v26
	v_cmp_nlt_f32_e32 vcc, s83, v45
	s_and_saveexec_b64 s[4:5], vcc
	s_xor_b64 s[4:5], exec, s[4:5]
	v_mul_f32_e32 v44, 0x3fb8aa3b, v45
	v_exp_f32_e32 v44, v44
	s_nop 0
	v_sub_f32_e32 v44, 1.0, v44
	s_andn2_saveexec_b64 s[4:5], s[4:5]
	v_fmamk_f32 v44, v45, 0x3c088889, v199
	v_fmaak_f32 v44, v45, v44, 0x3e2aaaab
	v_fma_f32 v44, v45, v44, 0.5
	v_fma_f32 v44, v45, v44, 1.0
	v_mul_f32_e64 v44, v44, -v45
	s_or_b64 exec, exec, s[4:5]
	v_add_f32_e32 v27, v27, v59
	v_mul_f32_e32 v27, 0xbfb8aa3b, v27
	v_exp_f32_e32 v27, v27
	s_nop 0
	v_add_f32_e32 v27, 1.0, v27
	v_rcp_f32_e32 v27, v27
	s_nop 0
	v_mul_f32_e32 v27, v27, v139
	v_add_f32_e32 v54, v27, v27
	v_cmp_nlt_f32_e32 vcc, s83, v54
	s_and_saveexec_b64 s[4:5], vcc
	s_xor_b64 s[4:5], exec, s[4:5]
	v_mul_f32_e32 v45, 0x3fb8aa3b, v54
	v_exp_f32_e32 v45, v45
	s_nop 0
	v_sub_f32_e32 v45, 1.0, v45
	s_andn2_saveexec_b64 s[4:5], s[4:5]
	v_fmamk_f32 v45, v54, 0x3c088889, v199
	v_fmaak_f32 v45, v54, v45, 0x3e2aaaab
	v_fma_f32 v45, v54, v45, 0.5
	v_fma_f32 v45, v54, v45, 1.0
	v_mul_f32_e64 v45, v45, -v54
	s_or_b64 exec, exec, s[4:5]
	v_add_f32_e32 v28, v28, v60
	v_mul_f32_e32 v28, 0xbfb8aa3b, v28
	v_exp_f32_e32 v28, v28
	s_nop 0
	v_add_f32_e32 v28, 1.0, v28
	v_rcp_f32_e32 v28, v28
	s_nop 0
	v_mul_f32_e32 v28, v28, v140
	v_add_f32_e32 v54, v28, v28
	v_cmp_nlt_f32_e32 vcc, s83, v54
	s_and_saveexec_b64 s[4:5], vcc
	s_xor_b64 s[4:5], exec, s[4:5]
	v_mul_f32_e32 v54, 0x3fb8aa3b, v54
	v_exp_f32_e32 v54, v54
	s_nop 0
	v_sub_f32_e32 v55, 1.0, v54
	s_andn2_saveexec_b64 s[4:5], s[4:5]
	v_fmamk_f32 v55, v54, 0x3c088889, v199
	v_fmaak_f32 v55, v54, v55, 0x3e2aaaab
	v_fma_f32 v55, v54, v55, 0.5
	v_fma_f32 v55, v54, v55, 1.0
	v_mul_f32_e64 v55, v55, -v54
	s_or_b64 exec, exec, s[4:5]
	v_add_f32_e32 v29, v29, v61
	v_mul_f32_e32 v29, 0xbfb8aa3b, v29
	v_exp_f32_e32 v29, v29
	s_nop 0
	v_add_f32_e32 v29, 1.0, v29
	v_rcp_f32_e32 v29, v29
	s_nop 0
	v_mul_f32_e32 v29, v29, v141
	v_add_f32_e32 v56, v29, v29
	v_cmp_nlt_f32_e32 vcc, s83, v56
	s_and_saveexec_b64 s[4:5], vcc
	s_xor_b64 s[4:5], exec, s[4:5]
	v_mul_f32_e32 v54, 0x3fb8aa3b, v56
	v_exp_f32_e32 v54, v54
	s_nop 0
	v_sub_f32_e32 v54, 1.0, v54
	s_andn2_saveexec_b64 s[4:5], s[4:5]
	v_fmamk_f32 v54, v56, 0x3c088889, v199
	v_fmaak_f32 v54, v56, v54, 0x3e2aaaab
	v_fma_f32 v54, v56, v54, 0.5
	v_fma_f32 v54, v56, v54, 1.0
	v_mul_f32_e64 v54, v54, -v56
	s_or_b64 exec, exec, s[4:5]
	v_add_f32_e32 v24, v24, v52
	v_mul_f32_e32 v24, 0xbfb8aa3b, v24
	v_exp_f32_e32 v24, v24
	v_add_f32_e32 v23, v23, v51
	v_mul_f32_e32 v23, 0xbfb8aa3b, v23
	v_add_f32_e32 v25, v25, v53
	v_add_f32_e32 v24, 1.0, v24
	v_exp_f32_e32 v23, v23
	v_rcp_f32_e32 v24, v24
	v_mul_f32_e32 v25, 0xbfb8aa3b, v25
	v_sqrt_f32_e32 v55, v55
	v_exp_f32_e32 v25, v25
	v_add_f32_e32 v22, v22, v50
	v_mul_f32_e32 v22, 0xbfb8aa3b, v22
	v_lshlrev_b32_e32 v56, 16, v37
	v_add_f32_e32 v23, 1.0, v23
	v_exp_f32_e32 v22, v22
	v_mul_f32_e32 v24, v24, v56
	v_rcp_f32_e32 v23, v23
	v_mul_f32_e32 v55, v24, v55
	v_add_f32_e32 v24, 1.0, v25
	v_sqrt_f32_e32 v25, v45
	v_add_f32_e32 v21, v21, v49
	v_mul_f32_e32 v21, 0xbfb8aa3b, v21
	v_and_b32_e32 v45, 0xffff0000, v36
	v_add_f32_e32 v22, 1.0, v22
	v_exp_f32_e32 v21, v21
	v_mul_f32_e32 v23, v23, v45
	v_rcp_f32_e32 v22, v22
	v_mul_f32_e32 v45, v23, v25
	v_sqrt_f32_e32 v23, v44
	v_add_f32_e32 v20, v20, v48
	v_mul_f32_e32 v20, 0xbfb8aa3b, v20
	v_lshlrev_b32_e32 v25, 16, v36
	v_add_f32_e32 v21, 1.0, v21
	v_exp_f32_e32 v20, v20
	v_mul_f32_e32 v22, v22, v25
	v_rcp_f32_e32 v21, v21
	v_mul_f32_e32 v36, v22, v23
	v_sqrt_f32_e32 v22, v43
	v_add_f32_e32 v19, v19, v47
	v_mul_f32_e32 v19, 0xbfb8aa3b, v19
	v_and_b32_e32 v23, 0xffff0000, v35
	v_add_f32_e32 v20, 1.0, v20
	v_exp_f32_e32 v19, v19
	v_mul_f32_e32 v21, v21, v23
	v_rcp_f32_e32 v20, v20
	v_add_f32_e32 v18, v18, v46
	v_mul_f32_e32 v43, v21, v22
	v_sqrt_f32_e32 v21, v42
	v_mul_f32_e32 v18, 0xbfb8aa3b, v18
	v_exp_f32_e32 v18, v18
	v_lshlrev_b32_e32 v22, 16, v35
	v_add_f32_e32 v19, 1.0, v19
	v_mul_f32_e32 v20, v20, v22
	v_rcp_f32_e32 v19, v19
	v_mul_f32_e32 v35, v20, v21
	v_sqrt_f32_e32 v21, v41
	v_add_f32_e32 v18, 1.0, v18
	v_and_b32_e32 v20, 0xffff0000, v34
	v_rcp_f32_e32 v18, v18
	v_mul_f32_e32 v19, v19, v20
	v_mul_f32_e32 v41, v19, v21
	v_sqrt_f32_e32 v19, v40
	v_rcp_f32_e32 v24, v24
	v_lshlrev_b32_e32 v20, 16, v34
	v_mul_f32_e32 v18, v18, v20
	v_sqrt_f32_e32 v20, v54
	v_mul_f32_e32 v34, v18, v19
	v_and_b32_e32 v18, 0xffff0000, v37
	v_mul_f32_e32 v18, v24, v18
	v_lshlrev_b64 v[22:23], 1, v[38:39]
	v_mul_f32_e32 v37, v18, v20
	v_lshl_add_u64 v[24:25], s[20:21], 0, v[22:23]
	v_cvt_pk_bf16_f32 v18, v30, v31
	v_cvt_pk_bf16_f32 v19, v32, v33
	v_cvt_pk_bf16_f32 v20, v26, v27
	v_cvt_pk_bf16_f32 v21, v28, v29
	global_store_dwordx4 v[24:25], v[18:21], off
	v_lshl_add_u64 v[22:23], s[22:23], 0, v[22:23]
	v_add_u32_e32 v0, 0xb0, v0
	v_cvt_pk_bf16_f32 v18, v34, v41
	v_cvt_pk_bf16_f32 v19, v35, v43
	v_cvt_pk_bf16_f32 v20, v36, v45
	v_cvt_pk_bf16_f32 v21, v55, v37
	global_store_dwordx4 v[22:23], v[18:21], off
	s_nop 1
	v_lshlrev_b64 v[18:19], 11, v[0:1]
	v_lshl_add_u64 v[22:23], v[18:19], 0, v[170:171]
	v_lshl_add_u64 v[18:19], v[22:23], 1, s[0:1]
	v_mov_b32_e32 v18, v184
	v_mov_b32_e32 v19, v185
	v_mov_b32_e32 v20, v186
	v_mov_b32_e32 v21, v187
	v_add_f32_e32 v0, v14, v66
	v_mul_f32_e32 v0, 0xbfb8aa3b, v0
	v_exp_f32_e32 v0, v0
	s_nop 0
	v_add_f32_e32 v0, 1.0, v0
	v_rcp_f32_e32 v0, v0
	s_nop 0
	v_mul_f32_e32 v0, v0, v142
	v_add_f32_e32 v24, v0, v0
	v_cmp_nlt_f32_e32 vcc, s83, v24
	s_and_saveexec_b64 s[4:5], vcc
	s_xor_b64 s[4:5], exec, s[4:5]
	v_mul_f32_e32 v14, 0x3fb8aa3b, v24
	v_exp_f32_e32 v14, v14
	s_nop 0
	v_sub_f32_e32 v14, 1.0, v14
	s_andn2_saveexec_b64 s[4:5], s[4:5]
	v_fmamk_f32 v14, v24, 0x3c088889, v199
	v_fmaak_f32 v14, v24, v14, 0x3e2aaaab
	v_fma_f32 v14, v24, v14, 0.5
	v_fma_f32 v14, v24, v14, 1.0
	v_mul_f32_e64 v14, v14, -v24
	s_or_b64 exec, exec, s[4:5]
	v_add_f32_e32 v15, v15, v67
	v_mul_f32_e32 v15, 0xbfb8aa3b, v15
	v_exp_f32_e32 v15, v15
	s_nop 0
	v_add_f32_e32 v15, 1.0, v15
	v_rcp_f32_e32 v15, v15
	s_nop 0
	v_mul_f32_e32 v15, v15, v143
	v_add_f32_e32 v25, v15, v15
	v_cmp_nlt_f32_e32 vcc, s83, v25
	s_and_saveexec_b64 s[4:5], vcc
	s_xor_b64 s[4:5], exec, s[4:5]
	v_mul_f32_e32 v24, 0x3fb8aa3b, v25
	v_exp_f32_e32 v24, v24
	s_nop 0
	v_sub_f32_e32 v24, 1.0, v24
	s_andn2_saveexec_b64 s[4:5], s[4:5]
	v_fmamk_f32 v24, v25, 0x3c088889, v199
	v_fmaak_f32 v24, v25, v24, 0x3e2aaaab
	v_fma_f32 v24, v25, v24, 0.5
	v_fma_f32 v24, v25, v24, 1.0
	v_mul_f32_e64 v24, v24, -v25
	s_or_b64 exec, exec, s[4:5]
	v_add_f32_e32 v16, v16, v68
	v_mul_f32_e32 v16, 0xbfb8aa3b, v16
	v_exp_f32_e32 v16, v16
	s_nop 0
	v_add_f32_e32 v16, 1.0, v16
	v_rcp_f32_e32 v16, v16
	s_nop 0
	v_mul_f32_e32 v16, v16, v144
	v_add_f32_e32 v26, v16, v16
	v_cmp_nlt_f32_e32 vcc, s83, v26
	s_and_saveexec_b64 s[4:5], vcc
	s_xor_b64 s[4:5], exec, s[4:5]
	v_mul_f32_e32 v25, 0x3fb8aa3b, v26
	v_exp_f32_e32 v25, v25
	s_nop 0
	v_sub_f32_e32 v25, 1.0, v25
	s_andn2_saveexec_b64 s[4:5], s[4:5]
	v_fmamk_f32 v25, v26, 0x3c088889, v199
	v_fmaak_f32 v25, v26, v25, 0x3e2aaaab
	v_fma_f32 v25, v26, v25, 0.5
	v_fma_f32 v25, v26, v25, 1.0
	v_mul_f32_e64 v25, v25, -v26
	s_or_b64 exec, exec, s[4:5]
	v_add_f32_e32 v17, v17, v69
	v_mul_f32_e32 v17, 0xbfb8aa3b, v17
	v_exp_f32_e32 v17, v17
	s_nop 0
	v_add_f32_e32 v17, 1.0, v17
	v_rcp_f32_e32 v17, v17
	s_nop 0
	v_mul_f32_e32 v17, v17, v145
	v_add_f32_e32 v27, v17, v17
	v_cmp_nlt_f32_e32 vcc, s83, v27
	s_and_saveexec_b64 s[4:5], vcc
	s_xor_b64 s[4:5], exec, s[4:5]
	v_mul_f32_e32 v26, 0x3fb8aa3b, v27
	v_exp_f32_e32 v26, v26
	s_nop 0
	v_sub_f32_e32 v26, 1.0, v26
	s_andn2_saveexec_b64 s[4:5], s[4:5]
	v_fmamk_f32 v26, v27, 0x3c088889, v199
	v_fmaak_f32 v26, v27, v26, 0x3e2aaaab
	v_fma_f32 v26, v27, v26, 0.5
	v_fma_f32 v26, v27, v26, 1.0
	v_mul_f32_e64 v26, v26, -v27
	s_or_b64 exec, exec, s[4:5]
	v_add_f32_e32 v10, v10, v58
	v_mul_f32_e32 v10, 0xbfb8aa3b, v10
	v_exp_f32_e32 v10, v10
	s_nop 0
	v_add_f32_e32 v10, 1.0, v10
	v_rcp_f32_e32 v10, v10
	s_nop 0
	v_mul_f32_e32 v10, v10, v138
	v_add_f32_e32 v28, v10, v10
	v_cmp_nlt_f32_e32 vcc, s83, v28
	s_and_saveexec_b64 s[4:5], vcc
	s_xor_b64 s[4:5], exec, s[4:5]
	v_mul_f32_e32 v27, 0x3fb8aa3b, v28
	v_exp_f32_e32 v27, v27
	s_nop 0
	v_sub_f32_e32 v27, 1.0, v27
	s_andn2_saveexec_b64 s[4:5], s[4:5]
	v_fmamk_f32 v27, v28, 0x3c088889, v199
	v_fmaak_f32 v27, v28, v27, 0x3e2aaaab
	v_fma_f32 v27, v28, v27, 0.5
	v_fma_f32 v27, v28, v27, 1.0
	v_mul_f32_e64 v27, v27, -v28
	s_or_b64 exec, exec, s[4:5]
	v_add_f32_e32 v11, v11, v59
	v_mul_f32_e32 v11, 0xbfb8aa3b, v11
	v_exp_f32_e32 v11, v11
	s_nop 0
	v_add_f32_e32 v11, 1.0, v11
	v_rcp_f32_e32 v11, v11
	s_nop 0
	v_mul_f32_e32 v11, v11, v139
	v_add_f32_e32 v29, v11, v11
	v_cmp_nlt_f32_e32 vcc, s83, v29
	s_and_saveexec_b64 s[4:5], vcc
	s_xor_b64 s[4:5], exec, s[4:5]
	v_mul_f32_e32 v28, 0x3fb8aa3b, v29
	v_exp_f32_e32 v28, v28
	s_nop 0
	v_sub_f32_e32 v28, 1.0, v28
	s_andn2_saveexec_b64 s[4:5], s[4:5]
	v_fmamk_f32 v28, v29, 0x3c088889, v199
	v_fmaak_f32 v28, v29, v28, 0x3e2aaaab
	v_fma_f32 v28, v29, v28, 0.5
	v_fma_f32 v28, v29, v28, 1.0
	v_mul_f32_e64 v28, v28, -v29
	s_or_b64 exec, exec, s[4:5]
	v_add_f32_e32 v12, v12, v60
	v_mul_f32_e32 v12, 0xbfb8aa3b, v12
	v_exp_f32_e32 v12, v12
	s_nop 0
	v_add_f32_e32 v12, 1.0, v12
	v_rcp_f32_e32 v12, v12
	s_nop 0
	v_mul_f32_e32 v12, v12, v140
	v_add_f32_e32 v29, v12, v12
	v_cmp_nlt_f32_e32 vcc, s83, v29
	s_and_saveexec_b64 s[4:5], vcc
	s_xor_b64 s[4:5], exec, s[4:5]
	v_mul_f32_e32 v29, 0x3fb8aa3b, v29
	v_exp_f32_e32 v29, v29
	s_nop 0
	v_sub_f32_e32 v30, 1.0, v29
	s_andn2_saveexec_b64 s[4:5], s[4:5]
	v_fmamk_f32 v30, v29, 0x3c088889, v199
	v_fmaak_f32 v30, v29, v30, 0x3e2aaaab
	v_fma_f32 v30, v29, v30, 0.5
	v_fma_f32 v30, v29, v30, 1.0
	v_mul_f32_e64 v30, v30, -v29
	s_or_b64 exec, exec, s[4:5]
	v_add_f32_e32 v13, v13, v61
	v_mul_f32_e32 v13, 0xbfb8aa3b, v13
	v_exp_f32_e32 v13, v13
	s_nop 0
	v_add_f32_e32 v13, 1.0, v13
	v_rcp_f32_e32 v13, v13
	s_nop 0
	v_mul_f32_e32 v13, v13, v141
	v_add_f32_e32 v31, v13, v13
	v_cmp_nlt_f32_e32 vcc, s83, v31
	s_and_saveexec_b64 s[4:5], vcc
	s_xor_b64 s[4:5], exec, s[4:5]
	v_mul_f32_e32 v29, 0x3fb8aa3b, v31
	v_exp_f32_e32 v29, v29
	s_nop 0
	v_sub_f32_e32 v29, 1.0, v29
	s_andn2_saveexec_b64 s[4:5], s[4:5]
	v_fmamk_f32 v29, v31, 0x3c088889, v199
	v_fmaak_f32 v29, v31, v29, 0x3e2aaaab
	v_fma_f32 v29, v31, v29, 0.5
	v_fma_f32 v29, v31, v29, 1.0
	v_mul_f32_e64 v29, v29, -v31
	s_or_b64 exec, exec, s[4:5]
	v_add_f32_e32 v7, v7, v51
	v_mul_f32_e32 v7, 0xbfb8aa3b, v7
	v_exp_f32_e32 v7, v7
	v_add_f32_e32 v6, v6, v50
	v_mul_f32_e32 v6, 0xbfb8aa3b, v6
	v_exp_f32_e32 v6, v6
	v_add_f32_e32 v7, 1.0, v7
	v_rcp_f32_e32 v7, v7
	v_add_f32_e32 v8, v8, v52
	v_lshlrev_b32_e32 v32, 16, v20
	v_and_b32_e32 v20, 0xffff0000, v20
	v_mul_f32_e32 v8, 0xbfb8aa3b, v8
	v_mul_f32_e32 v7, v7, v20
	v_sqrt_f32_e32 v20, v28
	v_add_f32_e32 v5, v5, v49
	v_exp_f32_e32 v8, v8
	v_mul_f32_e32 v5, 0xbfb8aa3b, v5
	v_add_f32_e32 v6, 1.0, v6
	v_exp_f32_e32 v5, v5
	v_rcp_f32_e32 v6, v6
	v_mul_f32_e32 v20, v7, v20
	v_sqrt_f32_e32 v7, v27
	v_add_f32_e32 v4, v4, v48
	v_add_f32_e32 v8, 1.0, v8
	v_mul_f32_e32 v4, 0xbfb8aa3b, v4
	v_rcp_f32_e32 v8, v8
	v_add_f32_e32 v5, 1.0, v5
	v_exp_f32_e32 v4, v4
	v_mul_f32_e32 v6, v6, v32
	v_rcp_f32_e32 v5, v5
	v_mul_f32_e32 v27, v6, v7
	v_sqrt_f32_e32 v6, v26
	v_add_f32_e32 v3, v3, v47
	v_lshlrev_b32_e32 v31, 16, v21
	v_mul_f32_e32 v3, 0xbfb8aa3b, v3
	v_mul_f32_e32 v8, v8, v31
	v_lshlrev_b32_e32 v31, 16, v19
	v_and_b32_e32 v19, 0xffff0000, v19
	v_add_f32_e32 v4, 1.0, v4
	v_exp_f32_e32 v3, v3
	v_mul_f32_e32 v5, v5, v19
	v_rcp_f32_e32 v4, v4
	v_add_f32_e32 v2, v2, v46
	v_add_f32_e32 v9, v9, v53
	v_mul_f32_e32 v19, v5, v6
	v_sqrt_f32_e32 v5, v25
	v_mul_f32_e32 v2, 0xbfb8aa3b, v2
	v_mul_f32_e32 v9, 0xbfb8aa3b, v9
	v_exp_f32_e32 v2, v2
	v_exp_f32_e32 v9, v9
	v_sqrt_f32_e32 v30, v30
	v_add_f32_e32 v3, 1.0, v3
	v_mul_f32_e32 v4, v4, v31
	v_rcp_f32_e32 v3, v3
	v_mul_f32_e32 v25, v4, v5
	v_sqrt_f32_e32 v4, v24
	v_add_f32_e32 v2, 1.0, v2
	v_add_f32_e32 v9, 1.0, v9
	v_mul_f32_e32 v30, v8, v30
	v_lshlrev_b32_e32 v8, 16, v18
	v_and_b32_e32 v18, 0xffff0000, v18
	v_rcp_f32_e32 v2, v2
	v_rcp_f32_e32 v9, v9
	v_mul_f32_e32 v3, v3, v18
	v_sqrt_f32_e32 v5, v14
	v_mul_f32_e32 v14, v3, v4
	v_sqrt_f32_e32 v3, v29
	v_and_b32_e32 v21, 0xffff0000, v21
	v_mul_f32_e32 v2, v2, v8
	v_mul_f32_e32 v18, v2, v5
	v_mul_f32_e32 v2, v9, v21
	v_lshlrev_b64 v[6:7], 1, v[22:23]
	v_mul_f32_e32 v21, v2, v3
	v_lshl_add_u64 v[8:9], s[20:21], 0, v[6:7]
	v_cvt_pk_bf16_f32 v2, v0, v15
	v_cvt_pk_bf16_f32 v3, v16, v17
	v_cvt_pk_bf16_f32 v4, v10, v11
	v_cvt_pk_bf16_f32 v5, v12, v13
	v_lshl_add_u64 v[6:7], s[22:23], 0, v[6:7]
	s_andn2_b64 vcc, exec, s[34:35]
	s_mov_b64 s[4:5], -1
	global_store_dwordx4 v[8:9], v[2:5], off
	s_nop 1
	v_cvt_pk_bf16_f32 v2, v18, v14
	v_cvt_pk_bf16_f32 v3, v25, v19
	v_cvt_pk_bf16_f32 v4, v27, v20
	v_cvt_pk_bf16_f32 v5, v30, v21
	global_store_dwordx4 v[6:7], v[2:5], off
	s_cbranch_vccnz .LBB0_733
	s_and_b64 vcc, exec, s[88:89]
	s_cbranch_vccnz .LBB0_732
	s_barrier
	s_branch .LBB0_732
